# MFMA phases trimmed: no mid-phase setprio pair, no redundant lgkmcnt(0) after the phase barrier
# baseline (speedup 1.0000x reference)
; #define PG8_STAGE(bufoff, gbase, voff) do { _Pragma("unroll") for (int _i = 0; _i < 2; ++_i) \
;         __builtin_amdgcn_global_load_lds((const unsigned*)((const char*)(gbase) + (voff)[_i]), (LAS unsigned*)(lds + (bufoff) + ldsw + _i * 8192), 16, 0, 0); } while (0)
; #define PG8_LDA(dst, b, h) do { _Pragma("unroll") for (int m = 0; m < 4; ++m) _Pragma("unroll") for (int k = 0; k < 2; ++k) dst[m][k] = *(const LAS bf16x8*)(lds + PG8_SA(b, h) + aoff + m * 2048 + k * 1024); } while (0)
; #define PG8_LDB(dst, b, h) do { _Pragma("unroll") for (int n = 0; n < 2; ++n) _Pragma("unroll") for (int k = 0; k < 2; ++k) dst[n][k] = *(const LAS bf16x8*)(lds + PG8_SB(b, h) + boff + n * 2048 + k * 1024); } while (0)
; #define PG8_MMA(ai, bj, At, Bt) do { __builtin_amdgcn_s_setprio(1); _Pragma("unroll") for (int m = 0; m < 4; ++m) _Pragma("unroll") for (int n = 0; n < 2; ++n) _Pragma("unroll") for (int k = 0; k < 2; ++k) \
;         acc[ai][bj][m][n] = __builtin_amdgcn_mfma_f32_16x16x32_bf16(Bt[n][k], At[m][k], acc[ai][bj][m][n], 0, 0, 0); __builtin_amdgcn_s_setprio(0); } while (0)
; #define PG8_WAIT_V(n) asm volatile("s_waitcnt vmcnt(" #n ")" ::: "memory")
; #define PG8_WAIT_L(n) asm volatile("s_waitcnt lgkmcnt(" #n ")" ::: "memory")
; #define PG8_BAR __builtin_amdgcn_s_barrier()
; #define PG8_SCHED __builtin_amdgcn_sched_barrier(0)
; template <class Epi, class Sched, bool APERM = false, bool HALFN = false>
; __device__ __forceinline__ void gemm_phase(LAS unsigned char* lds, const int tid_in, const int K, const Sched& S, const Epi& E) {
;     ...
;             PG8_LDB(B0, 0, 0); PG8_LDB(B1, 0, 1); PG8_SCHED; PG8_LDA(At, 0, 0); PG8_STAGE(PG8_SA(1, 1), a1 + hstepA, voffA);
;             PG8_WAIT_V(8); PG8_WAIT_L(0); PG8_BAR; PG8_MMA(0, 0, At, B0); if constexpr (!HALFN) PG8_MMA(0, 1, At, B1); PG8_BAR; PG8_SCHED;
;             PG8_LDA(At, 0, 1); PG8_STAGE(PG8_SB(0, 0), b2, voffB); PG8_STAGE(PG8_SB(0, 1), b2 + hstep, voffB); PG8_STAGE(PG8_SA(0, 0), a2, voffA);
;             PG8_WAIT_V(8); PG8_WAIT_L(0); PG8_BAR; PG8_MMA(1, 0, At, B0); if constexpr (!HALFN) PG8_MMA(1, 1, At, B1); PG8_BAR; PG8_SCHED;
.LBB0_346:
	s_add_u32 s4, s0, 0xfff80080
	s_addc_u32 s5, s1, -1
	s_add_i32 s44, 0, 0x10000
	s_cmp_eq_u32 s25, 28
	s_cselect_b32 s17, s19, s5
	s_cselect_b32 s16, s20, s4
	s_cselect_b32 s5, s21, s24
	s_cselect_b32 s4, s22, s23
	s_add_i32 s52, 0, 0x14000
	v_add_u32_e32 v180, s44, v139
	v_add_u32_e32 v196, s52, v139
	ds_read_b128 v[168:171], v180
	ds_read_b128 v[172:175], v180 offset:1024
	ds_read_b128 v[176:179], v180 offset:2048
	ds_read_b128 v[180:183], v180 offset:3072
	ds_read_b128 v[184:187], v196
	ds_read_b128 v[188:191], v196 offset:1024
	ds_read_b128 v[192:195], v196 offset:2048
	ds_read_b128 v[196:199], v196 offset:3072
	v_lshl_add_u64 v[232:233], s[0:1], 0, v[166:167]
	s_add_i32 m0, s38, 0xc000
	ds_read_b128 v[204:207], v141
	ds_read_b128 v[208:211], v141 offset:1024
	ds_read_b128 v[212:215], v141 offset:2048
	ds_read_b128 v[216:219], v141 offset:3072
	ds_read_b128 v[220:223], v141 offset:4096
	ds_read_b128 v[224:227], v141 offset:5120
	ds_read_b128 v[228:231], v141 offset:6144
	ds_read_b128 v[244:247], v141 offset:7168
	global_load_lds_dwordx4 v[232:233], off
	v_lshl_add_u64 v[232:233], s[0:1], 0, v[164:165]
	s_add_i32 m0, s38, 0xe000
	s_nop 0
	global_load_lds_dwordx4 v[232:233], off
	s_waitcnt vmcnt(8)
	s_waitcnt lgkmcnt(0)
	s_barrier
	s_setprio 1
	v_mfma_f32_16x16x32_bf16 v[124:127], v[168:171], v[204:207], v[124:127]
	v_mfma_f32_16x16x32_bf16 v[120:123], v[176:179], v[204:207], v[120:123]
	v_mfma_f32_16x16x32_bf16 v[108:111], v[168:171], v[212:215], v[108:111]
	v_mfma_f32_16x16x32_bf16 v[104:107], v[176:179], v[212:215], v[104:107]
	v_mfma_f32_16x16x32_bf16 v[92:95], v[168:171], v[220:223], v[92:95]
	v_mfma_f32_16x16x32_bf16 v[88:91], v[176:179], v[220:223], v[88:91]
	v_mfma_f32_16x16x32_bf16 v[76:79], v[168:171], v[228:231], v[76:79]
	v_mfma_f32_16x16x32_bf16 v[72:75], v[176:179], v[228:231], v[72:75]
	v_mfma_f32_16x16x32_bf16 v[124:127], v[172:175], v[208:211], v[124:127]
	v_mfma_f32_16x16x32_bf16 v[120:123], v[180:183], v[208:211], v[120:123]
	v_mfma_f32_16x16x32_bf16 v[108:111], v[172:175], v[216:219], v[108:111]
	v_mfma_f32_16x16x32_bf16 v[104:107], v[180:183], v[216:219], v[104:107]
	v_mfma_f32_16x16x32_bf16 v[92:95], v[172:175], v[224:227], v[92:95]
	v_mfma_f32_16x16x32_bf16 v[88:91], v[180:183], v[224:227], v[88:91]
	v_mfma_f32_16x16x32_bf16 v[76:79], v[172:175], v[244:247], v[76:79]
	v_mfma_f32_16x16x32_bf16 v[72:75], v[180:183], v[244:247], v[72:75]
	v_mfma_f32_16x16x32_bf16 v[116:119], v[184:187], v[204:207], v[116:119]
	v_mfma_f32_16x16x32_bf16 v[112:115], v[192:195], v[204:207], v[112:115]
	v_mfma_f32_16x16x32_bf16 v[100:103], v[184:187], v[212:215], v[100:103]
	v_mfma_f32_16x16x32_bf16 v[96:99], v[192:195], v[212:215], v[96:99]
	v_mfma_f32_16x16x32_bf16 v[84:87], v[184:187], v[220:223], v[84:87]
	v_mfma_f32_16x16x32_bf16 v[80:83], v[192:195], v[220:223], v[80:83]
	v_mfma_f32_16x16x32_bf16 v[68:71], v[184:187], v[228:231], v[68:71]
	v_mfma_f32_16x16x32_bf16 v[64:67], v[192:195], v[228:231], v[64:67]
	v_mfma_f32_16x16x32_bf16 v[116:119], v[188:191], v[208:211], v[116:119]
	v_mfma_f32_16x16x32_bf16 v[112:115], v[196:199], v[208:211], v[112:115]
	v_mfma_f32_16x16x32_bf16 v[100:103], v[188:191], v[216:219], v[100:103]
	v_mfma_f32_16x16x32_bf16 v[96:99], v[196:199], v[216:219], v[96:99]
	v_mfma_f32_16x16x32_bf16 v[84:87], v[188:191], v[224:227], v[84:87]
	v_mfma_f32_16x16x32_bf16 v[80:83], v[196:199], v[224:227], v[80:83]
	v_mfma_f32_16x16x32_bf16 v[68:71], v[188:191], v[244:247], v[68:71]
	v_mfma_f32_16x16x32_bf16 v[64:67], v[196:199], v[244:247], v[64:67]
	s_setprio 0
	s_barrier
	s_add_i32 s44, s44, s35
	v_lshl_add_u64 v[232:233], s[4:5], 0, v[130:131]
	s_mov_b32 m0, s44
	ds_read_b128 v[204:207], v141 offset:16384
	ds_read_b128 v[208:211], v141 offset:17408
	ds_read_b128 v[212:215], v141 offset:18432
	ds_read_b128 v[216:219], v141 offset:19456
	ds_read_b128 v[220:223], v141 offset:20480
	ds_read_b128 v[224:227], v141 offset:21504
	ds_read_b128 v[228:231], v141 offset:22528
	ds_read_b128 v[244:247], v141 offset:23552
	global_load_lds_dwordx4 v[232:233], off
	s_add_i32 m0, s44, 0x2000
	s_add_u32 s44, s4, 0x80000
	v_lshl_add_u64 v[248:249], s[4:5], 0, v[134:135]
	s_addc_u32 s45, s5, 0
	s_add_i32 s52, s52, s35
	global_load_lds_dwordx4 v[248:249], off
	v_lshl_add_u64 v[250:251], s[44:45], 0, v[130:131]
	s_mov_b32 m0, s52
	v_lshl_add_u64 v[252:253], s[16:17], 0, v[132:133]
	global_load_lds_dwordx4 v[250:251], off
	v_lshl_add_u64 v[250:251], s[44:45], 0, v[134:135]
	s_add_i32 m0, s52, 0x2000
	s_nop 0
	global_load_lds_dwordx4 v[250:251], off
	v_lshl_add_u64 v[250:251], s[16:17], 0, v[128:129]
	s_mov_b32 m0, s38
	s_nop 0
	global_load_lds_dwordx4 v[250:251], off
	s_mov_b32 m0, s39
	s_nop 0
	global_load_lds_dwordx4 v[252:253], off
	s_waitcnt vmcnt(8)
	s_waitcnt lgkmcnt(0)
	s_barrier
; #define PG8_STAGE(bufoff, gbase, voff) do { _Pragma("unroll") for (int _i = 0; _i < 2; ++_i) \
;         __builtin_amdgcn_global_load_lds((const unsigned*)((const char*)(gbase) + (voff)[_i]), (LAS unsigned*)(lds + (bufoff) + ldsw + _i * 8192), 16, 0, 0); } while (0)
; #define PG8_LDA(dst, b, h) do { _Pragma("unroll") for (int m = 0; m < 4; ++m) _Pragma("unroll") for (int k = 0; k < 2; ++k) dst[m][k] = *(const LAS bf16x8*)(lds + PG8_SA(b, h) + aoff + m * 2048 + k * 1024); } while (0)
; #define PG8_LDB(dst, b, h) do { _Pragma("unroll") for (int n = 0; n < 2; ++n) _Pragma("unroll") for (int k = 0; k < 2; ++k) dst[n][k] = *(const LAS bf16x8*)(lds + PG8_SB(b, h) + boff + n * 2048 + k * 1024); } while (0)
; #define PG8_MMA(ai, bj, At, Bt) do { __builtin_amdgcn_s_setprio(1); _Pragma("unroll") for (int m = 0; m < 4; ++m) _Pragma("unroll") for (int n = 0; n < 2; ++n) _Pragma("unroll") for (int k = 0; k < 2; ++k) \
;         acc[ai][bj][m][n] = __builtin_amdgcn_mfma_f32_16x16x32_bf16(Bt[n][k], At[m][k], acc[ai][bj][m][n], 0, 0, 0); __builtin_amdgcn_s_setprio(0); } while (0)
; #define PG8_WAIT_V(n) asm volatile("s_waitcnt vmcnt(" #n ")" ::: "memory")
; #define PG8_WAIT_L(n) asm volatile("s_waitcnt lgkmcnt(" #n ")" ::: "memory")
; #define PG8_BAR __builtin_amdgcn_s_barrier()
; #define PG8_SCHED __builtin_amdgcn_sched_barrier(0)
; template <class Epi, class Sched, bool APERM = false, bool HALFN = false>
; __device__ __forceinline__ void gemm_phase(LAS unsigned char* lds, const int tid_in, const int K, const Sched& S, const Epi& E) {
;     ...
;             PG8_WAIT_V(8); PG8_WAIT_L(0); PG8_BAR; PG8_MMA(1, 0, At, B0); if constexpr (!HALFN) PG8_MMA(1, 1, At, B1); PG8_BAR; PG8_SCHED;
;             PG8_LDB(B0, 1, 0); PG8_LDB(B1, 1, 1); PG8_SCHED; PG8_LDA(At, 1, 0); PG8_STAGE(PG8_SA(0, 1), a2 + hstepA, voffA);
;             PG8_WAIT_V(8); PG8_WAIT_L(0); PG8_BAR; PG8_MMA(0, 0, At, B0); if constexpr (!HALFN) PG8_MMA(0, 1, At, B1); PG8_BAR; PG8_SCHED;
;             PG8_LDA(At, 1, 1); PG8_STAGE(PG8_SB(1, 0), b3, voffB); PG8_STAGE(PG8_SB(1, 1), b3 + hstep, voffB); PG8_STAGE(PG8_SA(1, 0), a3, voffA);
	s_setprio 1
	v_mfma_f32_16x16x32_bf16 v[60:63], v[168:171], v[204:207], v[60:63]
	v_mfma_f32_16x16x32_bf16 v[56:59], v[176:179], v[204:207], v[56:59]
	v_mfma_f32_16x16x32_bf16 v[44:47], v[168:171], v[212:215], v[44:47]
	v_mfma_f32_16x16x32_bf16 v[40:43], v[176:179], v[212:215], v[40:43]
	v_mfma_f32_16x16x32_bf16 v[28:31], v[168:171], v[220:223], v[28:31]
	v_mfma_f32_16x16x32_bf16 v[24:27], v[176:179], v[220:223], v[24:27]
	v_mfma_f32_16x16x32_bf16 v[12:15], v[168:171], v[228:231], v[12:15]
	v_mfma_f32_16x16x32_bf16 v[8:11], v[176:179], v[228:231], v[8:11]
	v_mfma_f32_16x16x32_bf16 v[60:63], v[172:175], v[208:211], v[60:63]
	v_mfma_f32_16x16x32_bf16 v[56:59], v[180:183], v[208:211], v[56:59]
	v_mfma_f32_16x16x32_bf16 v[44:47], v[172:175], v[216:219], v[44:47]
	v_mfma_f32_16x16x32_bf16 v[40:43], v[180:183], v[216:219], v[40:43]
	v_mfma_f32_16x16x32_bf16 v[28:31], v[172:175], v[224:227], v[28:31]
	v_mfma_f32_16x16x32_bf16 v[24:27], v[180:183], v[224:227], v[24:27]
	v_mfma_f32_16x16x32_bf16 v[12:15], v[172:175], v[244:247], v[12:15]
	v_mfma_f32_16x16x32_bf16 v[8:11], v[180:183], v[244:247], v[8:11]
	v_mfma_f32_16x16x32_bf16 v[52:55], v[184:187], v[204:207], v[52:55]
	v_mfma_f32_16x16x32_bf16 v[48:51], v[192:195], v[204:207], v[48:51]
	v_mfma_f32_16x16x32_bf16 v[36:39], v[184:187], v[212:215], v[36:39]
	v_mfma_f32_16x16x32_bf16 v[32:35], v[192:195], v[212:215], v[32:35]
	v_mfma_f32_16x16x32_bf16 v[20:23], v[184:187], v[220:223], v[20:23]
	v_mfma_f32_16x16x32_bf16 v[16:19], v[192:195], v[220:223], v[16:19]
	v_mfma_f32_16x16x32_bf16 v[4:7], v[184:187], v[228:231], v[4:7]
	v_mfma_f32_16x16x32_bf16 v[0:3], v[192:195], v[228:231], v[0:3]
	v_mfma_f32_16x16x32_bf16 v[52:55], v[188:191], v[208:211], v[52:55]
	v_mfma_f32_16x16x32_bf16 v[48:51], v[196:199], v[208:211], v[48:51]
	v_mfma_f32_16x16x32_bf16 v[36:39], v[188:191], v[216:219], v[36:39]
	v_mfma_f32_16x16x32_bf16 v[32:35], v[196:199], v[216:219], v[32:35]
	v_mfma_f32_16x16x32_bf16 v[20:23], v[188:191], v[224:227], v[20:23]
	v_mfma_f32_16x16x32_bf16 v[16:19], v[196:199], v[224:227], v[16:19]
	v_mfma_f32_16x16x32_bf16 v[4:7], v[188:191], v[244:247], v[4:7]
	v_mfma_f32_16x16x32_bf16 v[0:3], v[196:199], v[244:247], v[0:3]
	s_setprio 0
	s_barrier
	s_add_i32 s44, 0, 0x18000
	s_add_i32 s45, 0, 0x1c000
	v_add_u32_e32 v180, s44, v139
	v_add_u32_e32 v196, s45, v139
	ds_read_b128 v[168:171], v180
	ds_read_b128 v[172:175], v180 offset:1024
	ds_read_b128 v[176:179], v180 offset:2048
	ds_read_b128 v[180:183], v180 offset:3072
	ds_read_b128 v[184:187], v196
	ds_read_b128 v[188:191], v196 offset:1024
	ds_read_b128 v[192:195], v196 offset:2048
	ds_read_b128 v[196:199], v196 offset:3072
	s_add_u32 s16, s16, 0x80000
	s_addc_u32 s17, s17, 0
	s_mov_b32 m0, s57
	v_lshl_add_u64 v[236:237], s[16:17], 0, v[128:129]
	ds_read_b128 v[204:207], v141 offset:32768
	ds_read_b128 v[208:211], v141 offset:33792
	ds_read_b128 v[212:215], v141 offset:34816
	ds_read_b128 v[216:219], v141 offset:35840
	ds_read_b128 v[220:223], v141 offset:36864
	ds_read_b128 v[224:227], v141 offset:37888
	ds_read_b128 v[228:231], v141 offset:38912
	ds_read_b128 v[244:247], v141 offset:39936
	global_load_lds_dwordx4 v[236:237], off
	v_lshl_add_u64 v[236:237], s[16:17], 0, v[132:133]
	s_mov_b32 m0, s70
	s_nop 0
	global_load_lds_dwordx4 v[236:237], off
	s_waitcnt vmcnt(8)
	s_waitcnt lgkmcnt(0)
	s_barrier
	s_setprio 1
	v_mfma_f32_16x16x32_bf16 v[124:127], v[168:171], v[204:207], v[124:127]
	v_mfma_f32_16x16x32_bf16 v[120:123], v[176:179], v[204:207], v[120:123]
	v_mfma_f32_16x16x32_bf16 v[108:111], v[168:171], v[212:215], v[108:111]
	v_mfma_f32_16x16x32_bf16 v[104:107], v[176:179], v[212:215], v[104:107]
	v_mfma_f32_16x16x32_bf16 v[92:95], v[168:171], v[220:223], v[92:95]
	v_mfma_f32_16x16x32_bf16 v[88:91], v[176:179], v[220:223], v[88:91]
	v_mfma_f32_16x16x32_bf16 v[76:79], v[168:171], v[228:231], v[76:79]
	v_mfma_f32_16x16x32_bf16 v[72:75], v[176:179], v[228:231], v[72:75]
	v_mfma_f32_16x16x32_bf16 v[124:127], v[172:175], v[208:211], v[124:127]
	v_mfma_f32_16x16x32_bf16 v[120:123], v[180:183], v[208:211], v[120:123]
	v_mfma_f32_16x16x32_bf16 v[108:111], v[172:175], v[216:219], v[108:111]
	v_mfma_f32_16x16x32_bf16 v[104:107], v[180:183], v[216:219], v[104:107]
	v_mfma_f32_16x16x32_bf16 v[92:95], v[172:175], v[224:227], v[92:95]
	v_mfma_f32_16x16x32_bf16 v[88:91], v[180:183], v[224:227], v[88:91]
	v_mfma_f32_16x16x32_bf16 v[76:79], v[172:175], v[244:247], v[76:79]
	v_mfma_f32_16x16x32_bf16 v[72:75], v[180:183], v[244:247], v[72:75]
	v_mfma_f32_16x16x32_bf16 v[116:119], v[184:187], v[204:207], v[116:119]
	v_mfma_f32_16x16x32_bf16 v[112:115], v[192:195], v[204:207], v[112:115]
	v_mfma_f32_16x16x32_bf16 v[100:103], v[184:187], v[212:215], v[100:103]
	v_mfma_f32_16x16x32_bf16 v[96:99], v[192:195], v[212:215], v[96:99]
	v_mfma_f32_16x16x32_bf16 v[84:87], v[184:187], v[220:223], v[84:87]
	v_mfma_f32_16x16x32_bf16 v[80:83], v[192:195], v[220:223], v[80:83]
	v_mfma_f32_16x16x32_bf16 v[68:71], v[184:187], v[228:231], v[68:71]
	v_mfma_f32_16x16x32_bf16 v[64:67], v[192:195], v[228:231], v[64:67]
	v_mfma_f32_16x16x32_bf16 v[116:119], v[188:191], v[208:211], v[116:119]
	v_mfma_f32_16x16x32_bf16 v[112:115], v[196:199], v[208:211], v[112:115]
	v_mfma_f32_16x16x32_bf16 v[100:103], v[188:191], v[216:219], v[100:103]
	v_mfma_f32_16x16x32_bf16 v[96:99], v[196:199], v[216:219], v[96:99]
	v_mfma_f32_16x16x32_bf16 v[84:87], v[188:191], v[224:227], v[84:87]
	v_mfma_f32_16x16x32_bf16 v[80:83], v[196:199], v[224:227], v[80:83]
	v_mfma_f32_16x16x32_bf16 v[68:71], v[188:191], v[244:247], v[68:71]
	v_mfma_f32_16x16x32_bf16 v[64:67], v[196:199], v[244:247], v[64:67]
	s_setprio 0
	s_barrier
; #define PG8_STAGE(bufoff, gbase, voff) do { _Pragma("unroll") for (int _i = 0; _i < 2; ++_i) \
;         __builtin_amdgcn_global_load_lds((const unsigned*)((const char*)(gbase) + (voff)[_i]), (LAS unsigned*)(lds + (bufoff) + ldsw + _i * 8192), 16, 0, 0); } while (0)
; #define PG8_LDA(dst, b, h) do { _Pragma("unroll") for (int m = 0; m < 4; ++m) _Pragma("unroll") for (int k = 0; k < 2; ++k) dst[m][k] = *(const LAS bf16x8*)(lds + PG8_SA(b, h) + aoff + m * 2048 + k * 1024); } while (0)
; #define PG8_MMA(ai, bj, At, Bt) do { __builtin_amdgcn_s_setprio(1); _Pragma("unroll") for (int m = 0; m < 4; ++m) _Pragma("unroll") for (int n = 0; n < 2; ++n) _Pragma("unroll") for (int k = 0; k < 2; ++k) \
;         acc[ai][bj][m][n] = __builtin_amdgcn_mfma_f32_16x16x32_bf16(Bt[n][k], At[m][k], acc[ai][bj][m][n], 0, 0, 0); __builtin_amdgcn_s_setprio(0); } while (0)
; #define PG8_WAIT_V(n) asm volatile("s_waitcnt vmcnt(" #n ")" ::: "memory")
; #define PG8_WAIT_L(n) asm volatile("s_waitcnt lgkmcnt(" #n ")" ::: "memory")
; #define PG8_BAR __builtin_amdgcn_s_barrier()
; #define PG8_SCHED __builtin_amdgcn_sched_barrier(0)
; template <class Epi, class Sched, bool APERM = false, bool HALFN = false>
; __device__ __forceinline__ void gemm_phase(LAS unsigned char* lds, const int tid_in, const int K, const Sched& S, const Epi& E) {
;     ...
;             PG8_LDA(At, 1, 1); PG8_STAGE(PG8_SB(1, 0), b3, voffB); PG8_STAGE(PG8_SB(1, 1), b3 + hstep, voffB); PG8_STAGE(PG8_SA(1, 0), a3, voffA);
;             PG8_WAIT_V(8); PG8_WAIT_L(0); PG8_BAR; PG8_MMA(1, 0, At, B0); if constexpr (!HALFN) PG8_MMA(1, 1, At, B1); PG8_BAR; PG8_SCHED;
;         }
;         if (wr == 0) PG8_BAR;
	s_add_i32 s16, s44, s35
	v_lshl_add_u64 v[232:233], v[232:233], 0, s[78:79]
	s_mov_b32 m0, s16
	ds_read_b128 v[204:207], v141 offset:49152
	ds_read_b128 v[208:211], v141 offset:50176
	ds_read_b128 v[212:215], v141 offset:51200
	ds_read_b128 v[216:219], v141 offset:52224
	ds_read_b128 v[220:223], v141 offset:53248
	ds_read_b128 v[224:227], v141 offset:54272
	ds_read_b128 v[228:231], v141 offset:55296
	ds_read_b128 v[244:247], v141 offset:56320
	global_load_lds_dwordx4 v[232:233], off
	s_add_i32 m0, s16, 0x2000
	s_add_u32 s4, s4, 0x80080
	v_lshl_add_u64 v[232:233], v[248:249], 0, s[78:79]
	s_addc_u32 s5, s5, 0
	s_add_i32 s16, s45, s35
	global_load_lds_dwordx4 v[232:233], off
	v_lshl_add_u64 v[232:233], s[4:5], 0, v[130:131]
	s_mov_b32 m0, s16
	s_nop 0
	global_load_lds_dwordx4 v[232:233], off
	v_lshl_add_u64 v[232:233], s[4:5], 0, v[134:135]
	s_add_i32 m0, s16, 0x2000
	s_nop 0
	global_load_lds_dwordx4 v[232:233], off
	v_lshl_add_u64 v[232:233], v[250:251], 0, s[78:79]
	s_mov_b32 m0, s71
	s_nop 0
	global_load_lds_dwordx4 v[232:233], off
	v_lshl_add_u64 v[232:233], v[252:253], 0, s[78:79]
	s_mov_b32 m0, s74
	s_nop 0
	global_load_lds_dwordx4 v[232:233], off
	s_waitcnt vmcnt(8)
	s_waitcnt lgkmcnt(0)
	s_barrier
	s_setprio 1
	v_mfma_f32_16x16x32_bf16 v[60:63], v[168:171], v[204:207], v[60:63]
	v_mfma_f32_16x16x32_bf16 v[56:59], v[176:179], v[204:207], v[56:59]
	v_mfma_f32_16x16x32_bf16 v[44:47], v[168:171], v[212:215], v[44:47]
	v_mfma_f32_16x16x32_bf16 v[40:43], v[176:179], v[212:215], v[40:43]
	v_mfma_f32_16x16x32_bf16 v[28:31], v[168:171], v[220:223], v[28:31]
	v_mfma_f32_16x16x32_bf16 v[24:27], v[176:179], v[220:223], v[24:27]
	v_mfma_f32_16x16x32_bf16 v[12:15], v[168:171], v[228:231], v[12:15]
	v_mfma_f32_16x16x32_bf16 v[8:11], v[176:179], v[228:231], v[8:11]
	v_mfma_f32_16x16x32_bf16 v[60:63], v[172:175], v[208:211], v[60:63]
	v_mfma_f32_16x16x32_bf16 v[56:59], v[180:183], v[208:211], v[56:59]
	v_mfma_f32_16x16x32_bf16 v[44:47], v[172:175], v[216:219], v[44:47]
	v_mfma_f32_16x16x32_bf16 v[40:43], v[180:183], v[216:219], v[40:43]
	v_mfma_f32_16x16x32_bf16 v[28:31], v[172:175], v[224:227], v[28:31]
	v_mfma_f32_16x16x32_bf16 v[24:27], v[180:183], v[224:227], v[24:27]
	v_mfma_f32_16x16x32_bf16 v[12:15], v[172:175], v[244:247], v[12:15]
	v_mfma_f32_16x16x32_bf16 v[8:11], v[180:183], v[244:247], v[8:11]
	v_mfma_f32_16x16x32_bf16 v[52:55], v[184:187], v[204:207], v[52:55]
	v_mfma_f32_16x16x32_bf16 v[48:51], v[192:195], v[204:207], v[48:51]
	v_mfma_f32_16x16x32_bf16 v[36:39], v[184:187], v[212:215], v[36:39]
	v_mfma_f32_16x16x32_bf16 v[32:35], v[192:195], v[212:215], v[32:35]
	v_mfma_f32_16x16x32_bf16 v[20:23], v[184:187], v[220:223], v[20:23]
	v_mfma_f32_16x16x32_bf16 v[16:19], v[192:195], v[220:223], v[16:19]
	v_mfma_f32_16x16x32_bf16 v[4:7], v[184:187], v[228:231], v[4:7]
	v_mfma_f32_16x16x32_bf16 v[0:3], v[192:195], v[228:231], v[0:3]
	v_mfma_f32_16x16x32_bf16 v[52:55], v[188:191], v[208:211], v[52:55]
	v_mfma_f32_16x16x32_bf16 v[48:51], v[196:199], v[208:211], v[48:51]
	v_mfma_f32_16x16x32_bf16 v[36:39], v[188:191], v[216:219], v[36:39]
	v_mfma_f32_16x16x32_bf16 v[32:35], v[196:199], v[216:219], v[32:35]
	v_mfma_f32_16x16x32_bf16 v[20:23], v[188:191], v[224:227], v[20:23]
	v_mfma_f32_16x16x32_bf16 v[16:19], v[196:199], v[224:227], v[16:19]
	v_mfma_f32_16x16x32_bf16 v[4:7], v[188:191], v[244:247], v[4:7]
	v_mfma_f32_16x16x32_bf16 v[0:3], v[196:199], v[244:247], v[0:3]
	s_setprio 0
	s_barrier
	s_add_i32 s25, s25, 2
	s_add_u32 s23, s23, 0x100
	s_addc_u32 s24, s24, 0
	s_add_u32 s0, s0, 0x100
	s_addc_u32 s1, s1, 0
	s_cmp_gt_u32 s25, 29
	s_cbranch_scc0 .LBB0_346
	s_and_b64 vcc, exec, s[6:7]
	s_cbranch_vccz .LBB0_349
	s_barrier

; #define PG8_STAGE(bufoff, gbase, voff) do { _Pragma("unroll") for (int _i = 0; _i < 2; ++_i) \
;         __builtin_amdgcn_global_load_lds((const unsigned*)((const char*)(gbase) + (voff)[_i]), (LAS unsigned*)(lds + (bufoff) + ldsw + _i * 8192), 16, 0, 0); } while (0)
; #define PG8_LDA(dst, b, h) do { _Pragma("unroll") for (int m = 0; m < 4; ++m) _Pragma("unroll") for (int k = 0; k < 2; ++k) dst[m][k] = *(const LAS bf16x8*)(lds + PG8_SA(b, h) + aoff + m * 2048 + k * 1024); } while (0)
; #define PG8_LDB(dst, b, h) do { _Pragma("unroll") for (int n = 0; n < 2; ++n) _Pragma("unroll") for (int k = 0; k < 2; ++k) dst[n][k] = *(const LAS bf16x8*)(lds + PG8_SB(b, h) + boff + n * 2048 + k * 1024); } while (0)
; #define PG8_MMA(ai, bj, At, Bt) do { __builtin_amdgcn_s_setprio(1); _Pragma("unroll") for (int m = 0; m < 4; ++m) _Pragma("unroll") for (int n = 0; n < 2; ++n) _Pragma("unroll") for (int k = 0; k < 2; ++k) \
;         acc[ai][bj][m][n] = __builtin_amdgcn_mfma_f32_16x16x32_bf16(Bt[n][k], At[m][k], acc[ai][bj][m][n], 0, 0, 0); __builtin_amdgcn_s_setprio(0); } while (0)
; #define PG8_WAIT_V(n) asm volatile("s_waitcnt vmcnt(" #n ")" ::: "memory")
; #define PG8_WAIT_L(n) asm volatile("s_waitcnt lgkmcnt(" #n ")" ::: "memory")
; #define PG8_BAR __builtin_amdgcn_s_barrier()
; template <class Epi, class Sched, bool APERM = false, bool HALFN = false>
; __device__ __forceinline__ void gemm_phase(LAS unsigned char* lds, const int tid_in, const int K, const Sched& S, const Epi& E) {
;     ...
;             const bool last = (t == nt - 2);
;             const char* a1 = cA + (size_t)(t + 1) * kstep;
;             const char* a2 = last ? nA : cA + (size_t)(t + 2) * kstep; const char* b2 = last ? nB : cB + (size_t)(t + 2) * kstep;
;             const char* a3 = a2 + kstep; const char* b3 = b2 + kstep;
;             PG8_LDB(B0, 0, 0); PG8_LDB(B1, 0, 1); PG8_SCHED; PG8_LDA(At, 0, 0); PG8_STAGE(PG8_SA(1, 1), a1 + hstepA, voffA);
;             PG8_WAIT_V(8); PG8_WAIT_L(0); PG8_BAR; PG8_MMA(0, 0, At, B0); if constexpr (!HALFN) PG8_MMA(0, 1, At, B1); PG8_BAR; PG8_SCHED;
;             PG8_LDA(At, 0, 1); PG8_STAGE(PG8_SB(0, 0), b2, voffB); PG8_STAGE(PG8_SB(0, 1), b2 + hstep, voffB); PG8_STAGE(PG8_SA(0, 0), a2, voffA);
;             PG8_WAIT_V(8); PG8_WAIT_L(0); PG8_BAR; PG8_MMA(1, 0, At, B0); if constexpr (!HALFN) PG8_MMA(1, 1, At, B1); PG8_BAR; PG8_SCHED;
.LBB0_682:
	s_add_u32 s18, s16, 0xfff80080
	s_addc_u32 s19, s17, -1
	s_add_i32 s57, 0, 0x10000
	s_cmp_eq_u32 s53, 28
	s_cselect_b32 s21, s11, s19
	s_cselect_b32 s20, s10, s18
	s_cselect_b32 s19, s13, s52
	s_cselect_b32 s18, s12, s45
	s_add_i32 s72, 0, 0x14000
	v_add_u32_e32 v128, s57, v220
	v_add_u32_e32 v156, s72, v220
	ds_read_b128 v[112:115], v128
	ds_read_b128 v[116:119], v128 offset:1024
	ds_read_b128 v[120:123], v128 offset:2048
	ds_read_b128 v[128:131], v128 offset:3072
	ds_read_b128 v[136:139], v156
	ds_read_b128 v[140:143], v156 offset:1024
	ds_read_b128 v[144:147], v156 offset:2048
	ds_read_b128 v[156:159], v156 offset:3072
	v_lshl_add_u64 v[208:209], s[16:17], 0, v[198:199]
	s_add_i32 m0, s29, 0xc000
	ds_read_b128 v[160:163], v226
	ds_read_b128 v[164:167], v226 offset:1024
	ds_read_b128 v[168:171], v226 offset:2048
	ds_read_b128 v[172:175], v226 offset:3072
	ds_read_b128 v[176:179], v226 offset:4096
	ds_read_b128 v[180:183], v226 offset:5120
	ds_read_b128 v[184:187], v226 offset:6144
	ds_read_b128 v[204:207], v226 offset:7168
	global_load_lds_dwordx4 v[208:209], off
	v_lshl_add_u64 v[208:209], s[16:17], 0, v[196:197]
	s_add_i32 m0, s29, 0xe000
	s_nop 0
	global_load_lds_dwordx4 v[208:209], off
	s_waitcnt vmcnt(8)
	s_waitcnt lgkmcnt(0)
	s_barrier
	s_setprio 1
	v_mfma_f32_16x16x32_bf16 v[152:155], v[112:115], v[160:163], v[152:155]
	v_mfma_f32_16x16x32_bf16 v[148:151], v[120:123], v[160:163], v[148:151]
	v_mfma_f32_16x16x32_bf16 v[108:111], v[112:115], v[168:171], v[108:111]
	v_mfma_f32_16x16x32_bf16 v[104:107], v[120:123], v[168:171], v[104:107]
	v_mfma_f32_16x16x32_bf16 v[92:95], v[112:115], v[176:179], v[92:95]
	v_mfma_f32_16x16x32_bf16 v[88:91], v[120:123], v[176:179], v[88:91]
	v_mfma_f32_16x16x32_bf16 v[76:79], v[112:115], v[184:187], v[76:79]
	v_mfma_f32_16x16x32_bf16 v[72:75], v[120:123], v[184:187], v[72:75]
	v_mfma_f32_16x16x32_bf16 v[152:155], v[116:119], v[164:167], v[152:155]
	v_mfma_f32_16x16x32_bf16 v[148:151], v[128:131], v[164:167], v[148:151]
	v_mfma_f32_16x16x32_bf16 v[108:111], v[116:119], v[172:175], v[108:111]
	v_mfma_f32_16x16x32_bf16 v[104:107], v[128:131], v[172:175], v[104:107]
	v_mfma_f32_16x16x32_bf16 v[92:95], v[116:119], v[180:183], v[92:95]
	v_mfma_f32_16x16x32_bf16 v[88:91], v[128:131], v[180:183], v[88:91]
	v_mfma_f32_16x16x32_bf16 v[76:79], v[116:119], v[204:207], v[76:79]
	v_mfma_f32_16x16x32_bf16 v[72:75], v[128:131], v[204:207], v[72:75]
	v_mfma_f32_16x16x32_bf16 v[132:135], v[136:139], v[160:163], v[132:135]
	v_mfma_f32_16x16x32_bf16 v[124:127], v[144:147], v[160:163], v[124:127]
	v_mfma_f32_16x16x32_bf16 v[100:103], v[136:139], v[168:171], v[100:103]
	v_mfma_f32_16x16x32_bf16 v[96:99], v[144:147], v[168:171], v[96:99]
	v_mfma_f32_16x16x32_bf16 v[84:87], v[136:139], v[176:179], v[84:87]
	v_mfma_f32_16x16x32_bf16 v[80:83], v[144:147], v[176:179], v[80:83]
	v_mfma_f32_16x16x32_bf16 v[68:71], v[136:139], v[184:187], v[68:71]
	v_mfma_f32_16x16x32_bf16 v[64:67], v[144:147], v[184:187], v[64:67]
	v_mfma_f32_16x16x32_bf16 v[132:135], v[140:143], v[164:167], v[132:135]
	v_mfma_f32_16x16x32_bf16 v[124:127], v[156:159], v[164:167], v[124:127]
	v_mfma_f32_16x16x32_bf16 v[100:103], v[140:143], v[172:175], v[100:103]
	v_mfma_f32_16x16x32_bf16 v[96:99], v[156:159], v[172:175], v[96:99]
	v_mfma_f32_16x16x32_bf16 v[84:87], v[140:143], v[180:183], v[84:87]
	v_mfma_f32_16x16x32_bf16 v[80:83], v[156:159], v[180:183], v[80:83]
	v_mfma_f32_16x16x32_bf16 v[68:71], v[140:143], v[204:207], v[68:71]
	v_mfma_f32_16x16x32_bf16 v[64:67], v[156:159], v[204:207], v[64:67]
	s_setprio 0
	s_barrier
	s_add_i32 s57, s57, s28
	v_lshl_add_u64 v[208:209], s[18:19], 0, v[200:201]
	s_mov_b32 m0, s57
	ds_read_b128 v[160:163], v226 offset:16384
	ds_read_b128 v[164:167], v226 offset:17408
	ds_read_b128 v[168:171], v226 offset:18432
	ds_read_b128 v[172:175], v226 offset:19456
	ds_read_b128 v[176:179], v226 offset:20480
	ds_read_b128 v[180:183], v226 offset:21504
	ds_read_b128 v[184:187], v226 offset:22528
	ds_read_b128 v[204:207], v226 offset:23552
	global_load_lds_dwordx4 v[208:209], off
	s_add_i32 m0, s57, 0x2000
	s_add_u32 s70, s18, 0x80000
	v_lshl_add_u64 v[210:211], s[18:19], 0, v[192:193]
	s_addc_u32 s71, s19, 0
	s_add_i32 s57, s72, s28
	global_load_lds_dwordx4 v[210:211], off
	v_lshl_add_u64 v[212:213], s[70:71], 0, v[200:201]
	s_mov_b32 m0, s57
	v_lshl_add_u64 v[214:215], s[20:21], 0, v[190:191]
	global_load_lds_dwordx4 v[212:213], off
	v_lshl_add_u64 v[212:213], s[70:71], 0, v[192:193]
	s_add_i32 m0, s57, 0x2000
	s_nop 0
	global_load_lds_dwordx4 v[212:213], off
	v_lshl_add_u64 v[212:213], s[20:21], 0, v[188:189]
	s_mov_b32 m0, s29
	s_nop 0
	global_load_lds_dwordx4 v[212:213], off
	s_mov_b32 m0, s30
	s_nop 0
	global_load_lds_dwordx4 v[214:215], off
	s_waitcnt vmcnt(8)
	s_waitcnt lgkmcnt(0)
	s_barrier
; #define PG8_STAGE(bufoff, gbase, voff) do { _Pragma("unroll") for (int _i = 0; _i < 2; ++_i) \
;         __builtin_amdgcn_global_load_lds((const unsigned*)((const char*)(gbase) + (voff)[_i]), (LAS unsigned*)(lds + (bufoff) + ldsw + _i * 8192), 16, 0, 0); } while (0)
; #define PG8_LDA(dst, b, h) do { _Pragma("unroll") for (int m = 0; m < 4; ++m) _Pragma("unroll") for (int k = 0; k < 2; ++k) dst[m][k] = *(const LAS bf16x8*)(lds + PG8_SA(b, h) + aoff + m * 2048 + k * 1024); } while (0)
; #define PG8_LDB(dst, b, h) do { _Pragma("unroll") for (int n = 0; n < 2; ++n) _Pragma("unroll") for (int k = 0; k < 2; ++k) dst[n][k] = *(const LAS bf16x8*)(lds + PG8_SB(b, h) + boff + n * 2048 + k * 1024); } while (0)
; #define PG8_MMA(ai, bj, At, Bt) do { __builtin_amdgcn_s_setprio(1); _Pragma("unroll") for (int m = 0; m < 4; ++m) _Pragma("unroll") for (int n = 0; n < 2; ++n) _Pragma("unroll") for (int k = 0; k < 2; ++k) \
;         acc[ai][bj][m][n] = __builtin_amdgcn_mfma_f32_16x16x32_bf16(Bt[n][k], At[m][k], acc[ai][bj][m][n], 0, 0, 0); __builtin_amdgcn_s_setprio(0); } while (0)
; #define PG8_WAIT_V(n) asm volatile("s_waitcnt vmcnt(" #n ")" ::: "memory")
; #define PG8_WAIT_L(n) asm volatile("s_waitcnt lgkmcnt(" #n ")" ::: "memory")
; #define PG8_BAR __builtin_amdgcn_s_barrier()
; #define PG8_SCHED __builtin_amdgcn_sched_barrier(0)
; template <class Epi, class Sched, bool APERM = false, bool HALFN = false>
; __device__ __forceinline__ void gemm_phase(LAS unsigned char* lds, const int tid_in, const int K, const Sched& S, const Epi& E) {
;     ...
;             PG8_WAIT_V(8); PG8_WAIT_L(0); PG8_BAR; PG8_MMA(1, 0, At, B0); if constexpr (!HALFN) PG8_MMA(1, 1, At, B1); PG8_BAR; PG8_SCHED;
;             PG8_LDB(B0, 1, 0); PG8_LDB(B1, 1, 1); PG8_SCHED; PG8_LDA(At, 1, 0); PG8_STAGE(PG8_SA(0, 1), a2 + hstepA, voffA);
;             PG8_WAIT_V(8); PG8_WAIT_L(0); PG8_BAR; PG8_MMA(0, 0, At, B0); if constexpr (!HALFN) PG8_MMA(0, 1, At, B1); PG8_BAR; PG8_SCHED;
	s_setprio 1
	v_mfma_f32_16x16x32_bf16 v[60:63], v[112:115], v[160:163], v[60:63]
	v_mfma_f32_16x16x32_bf16 v[56:59], v[120:123], v[160:163], v[56:59]
	v_mfma_f32_16x16x32_bf16 v[44:47], v[112:115], v[168:171], v[44:47]
	v_mfma_f32_16x16x32_bf16 v[40:43], v[120:123], v[168:171], v[40:43]
	v_mfma_f32_16x16x32_bf16 v[28:31], v[112:115], v[176:179], v[28:31]
	v_mfma_f32_16x16x32_bf16 v[24:27], v[120:123], v[176:179], v[24:27]
	v_mfma_f32_16x16x32_bf16 v[12:15], v[112:115], v[184:187], v[12:15]
	v_mfma_f32_16x16x32_bf16 v[8:11], v[120:123], v[184:187], v[8:11]
	v_mfma_f32_16x16x32_bf16 v[60:63], v[116:119], v[164:167], v[60:63]
	v_mfma_f32_16x16x32_bf16 v[56:59], v[128:131], v[164:167], v[56:59]
	v_mfma_f32_16x16x32_bf16 v[44:47], v[116:119], v[172:175], v[44:47]
	v_mfma_f32_16x16x32_bf16 v[40:43], v[128:131], v[172:175], v[40:43]
	v_mfma_f32_16x16x32_bf16 v[28:31], v[116:119], v[180:183], v[28:31]
	v_mfma_f32_16x16x32_bf16 v[24:27], v[128:131], v[180:183], v[24:27]
	v_mfma_f32_16x16x32_bf16 v[12:15], v[116:119], v[204:207], v[12:15]
	v_mfma_f32_16x16x32_bf16 v[8:11], v[128:131], v[204:207], v[8:11]
	v_mfma_f32_16x16x32_bf16 v[52:55], v[136:139], v[160:163], v[52:55]
	v_mfma_f32_16x16x32_bf16 v[48:51], v[144:147], v[160:163], v[48:51]
	v_mfma_f32_16x16x32_bf16 v[36:39], v[136:139], v[168:171], v[36:39]
	v_mfma_f32_16x16x32_bf16 v[32:35], v[144:147], v[168:171], v[32:35]
	v_mfma_f32_16x16x32_bf16 v[20:23], v[136:139], v[176:179], v[20:23]
	v_mfma_f32_16x16x32_bf16 v[16:19], v[144:147], v[176:179], v[16:19]
	v_mfma_f32_16x16x32_bf16 v[4:7], v[136:139], v[184:187], v[4:7]
	v_mfma_f32_16x16x32_bf16 v[0:3], v[144:147], v[184:187], v[0:3]
	v_mfma_f32_16x16x32_bf16 v[52:55], v[140:143], v[164:167], v[52:55]
	v_mfma_f32_16x16x32_bf16 v[48:51], v[156:159], v[164:167], v[48:51]
	v_mfma_f32_16x16x32_bf16 v[36:39], v[140:143], v[172:175], v[36:39]
	v_mfma_f32_16x16x32_bf16 v[32:35], v[156:159], v[172:175], v[32:35]
	v_mfma_f32_16x16x32_bf16 v[20:23], v[140:143], v[180:183], v[20:23]
	v_mfma_f32_16x16x32_bf16 v[16:19], v[156:159], v[180:183], v[16:19]
	v_mfma_f32_16x16x32_bf16 v[4:7], v[140:143], v[204:207], v[4:7]
	v_mfma_f32_16x16x32_bf16 v[0:3], v[156:159], v[204:207], v[0:3]
	s_setprio 0
	s_barrier
	s_add_i32 s57, 0, 0x18000
	s_add_i32 s70, 0, 0x1c000
	v_add_u32_e32 v128, s57, v220
	v_add_u32_e32 v156, s70, v220
	ds_read_b128 v[112:115], v128
	ds_read_b128 v[116:119], v128 offset:1024
	ds_read_b128 v[120:123], v128 offset:2048
	ds_read_b128 v[128:131], v128 offset:3072
	ds_read_b128 v[136:139], v156
	ds_read_b128 v[140:143], v156 offset:1024
	ds_read_b128 v[144:147], v156 offset:2048
	ds_read_b128 v[156:159], v156 offset:3072
	s_add_u32 s20, s20, 0x80000
	s_addc_u32 s21, s21, 0
	s_mov_b32 m0, s31
	v_lshl_add_u64 v[216:217], s[20:21], 0, v[188:189]
	ds_read_b128 v[160:163], v226 offset:32768
	ds_read_b128 v[164:167], v226 offset:33792
	ds_read_b128 v[168:171], v226 offset:34816
	ds_read_b128 v[172:175], v226 offset:35840
	ds_read_b128 v[176:179], v226 offset:36864
	ds_read_b128 v[180:183], v226 offset:37888
	ds_read_b128 v[184:187], v226 offset:38912
	ds_read_b128 v[204:207], v226 offset:39936
	global_load_lds_dwordx4 v[216:217], off
	v_lshl_add_u64 v[216:217], s[20:21], 0, v[190:191]
	s_mov_b32 m0, s34
	s_nop 0
	global_load_lds_dwordx4 v[216:217], off
	s_waitcnt vmcnt(8)
	s_waitcnt lgkmcnt(0)
	s_barrier
	s_setprio 1
	v_mfma_f32_16x16x32_bf16 v[152:155], v[112:115], v[160:163], v[152:155]
	v_mfma_f32_16x16x32_bf16 v[148:151], v[120:123], v[160:163], v[148:151]
	v_mfma_f32_16x16x32_bf16 v[108:111], v[112:115], v[168:171], v[108:111]
	v_mfma_f32_16x16x32_bf16 v[104:107], v[120:123], v[168:171], v[104:107]
	v_mfma_f32_16x16x32_bf16 v[92:95], v[112:115], v[176:179], v[92:95]
	v_mfma_f32_16x16x32_bf16 v[88:91], v[120:123], v[176:179], v[88:91]
	v_mfma_f32_16x16x32_bf16 v[76:79], v[112:115], v[184:187], v[76:79]
	v_mfma_f32_16x16x32_bf16 v[72:75], v[120:123], v[184:187], v[72:75]
	v_mfma_f32_16x16x32_bf16 v[152:155], v[116:119], v[164:167], v[152:155]
	v_mfma_f32_16x16x32_bf16 v[148:151], v[128:131], v[164:167], v[148:151]
	v_mfma_f32_16x16x32_bf16 v[108:111], v[116:119], v[172:175], v[108:111]
	v_mfma_f32_16x16x32_bf16 v[104:107], v[128:131], v[172:175], v[104:107]
	v_mfma_f32_16x16x32_bf16 v[92:95], v[116:119], v[180:183], v[92:95]
	v_mfma_f32_16x16x32_bf16 v[88:91], v[128:131], v[180:183], v[88:91]
	v_mfma_f32_16x16x32_bf16 v[76:79], v[116:119], v[204:207], v[76:79]
	v_mfma_f32_16x16x32_bf16 v[72:75], v[128:131], v[204:207], v[72:75]
	v_mfma_f32_16x16x32_bf16 v[132:135], v[136:139], v[160:163], v[132:135]
	v_mfma_f32_16x16x32_bf16 v[124:127], v[144:147], v[160:163], v[124:127]
	v_mfma_f32_16x16x32_bf16 v[100:103], v[136:139], v[168:171], v[100:103]
	v_mfma_f32_16x16x32_bf16 v[96:99], v[144:147], v[168:171], v[96:99]
	v_mfma_f32_16x16x32_bf16 v[84:87], v[136:139], v[176:179], v[84:87]
	v_mfma_f32_16x16x32_bf16 v[80:83], v[144:147], v[176:179], v[80:83]
	v_mfma_f32_16x16x32_bf16 v[68:71], v[136:139], v[184:187], v[68:71]
	v_mfma_f32_16x16x32_bf16 v[64:67], v[144:147], v[184:187], v[64:67]
	v_mfma_f32_16x16x32_bf16 v[132:135], v[140:143], v[164:167], v[132:135]
	v_mfma_f32_16x16x32_bf16 v[124:127], v[156:159], v[164:167], v[124:127]
	v_mfma_f32_16x16x32_bf16 v[100:103], v[140:143], v[172:175], v[100:103]
	v_mfma_f32_16x16x32_bf16 v[96:99], v[156:159], v[172:175], v[96:99]
	v_mfma_f32_16x16x32_bf16 v[84:87], v[140:143], v[180:183], v[84:87]
	v_mfma_f32_16x16x32_bf16 v[80:83], v[156:159], v[180:183], v[80:83]
	v_mfma_f32_16x16x32_bf16 v[68:71], v[140:143], v[204:207], v[68:71]
	v_mfma_f32_16x16x32_bf16 v[64:67], v[156:159], v[204:207], v[64:67]
	s_setprio 0
	s_barrier
; #define PG8_STAGE(bufoff, gbase, voff) do { _Pragma("unroll") for (int _i = 0; _i < 2; ++_i) \
;         __builtin_amdgcn_global_load_lds((const unsigned*)((const char*)(gbase) + (voff)[_i]), (LAS unsigned*)(lds + (bufoff) + ldsw + _i * 8192), 16, 0, 0); } while (0)
; #define PG8_LDA(dst, b, h) do { _Pragma("unroll") for (int m = 0; m < 4; ++m) _Pragma("unroll") for (int k = 0; k < 2; ++k) dst[m][k] = *(const LAS bf16x8*)(lds + PG8_SA(b, h) + aoff + m * 2048 + k * 1024); } while (0)
; #define PG8_MMA(ai, bj, At, Bt) do { __builtin_amdgcn_s_setprio(1); _Pragma("unroll") for (int m = 0; m < 4; ++m) _Pragma("unroll") for (int n = 0; n < 2; ++n) _Pragma("unroll") for (int k = 0; k < 2; ++k) \
;         acc[ai][bj][m][n] = __builtin_amdgcn_mfma_f32_16x16x32_bf16(Bt[n][k], At[m][k], acc[ai][bj][m][n], 0, 0, 0); __builtin_amdgcn_s_setprio(0); } while (0)
; #define PG8_WAIT_V(n) asm volatile("s_waitcnt vmcnt(" #n ")" ::: "memory")
; #define PG8_WAIT_L(n) asm volatile("s_waitcnt lgkmcnt(" #n ")" ::: "memory")
; #define PG8_BAR __builtin_amdgcn_s_barrier()
; #define PG8_SCHED __builtin_amdgcn_sched_barrier(0)
; template <class Epi, class Sched, bool APERM = false, bool HALFN = false>
; __device__ __forceinline__ void gemm_phase(LAS unsigned char* lds, const int tid_in, const int K, const Sched& S, const Epi& E) {
;     ...
;             PG8_LDA(At, 1, 1); PG8_STAGE(PG8_SB(1, 0), b3, voffB); PG8_STAGE(PG8_SB(1, 1), b3 + hstep, voffB); PG8_STAGE(PG8_SA(1, 0), a3, voffA);
;             PG8_WAIT_V(8); PG8_WAIT_L(0); PG8_BAR; PG8_MMA(1, 0, At, B0); if constexpr (!HALFN) PG8_MMA(1, 1, At, B1); PG8_BAR; PG8_SCHED;
;         }
;         if (wr == 0) PG8_BAR;
	s_add_i32 s20, s57, s28
	v_lshl_add_u64 v[208:209], v[208:209], 0, s[78:79]
	s_mov_b32 m0, s20
	ds_read_b128 v[160:163], v226 offset:49152
	ds_read_b128 v[164:167], v226 offset:50176
	ds_read_b128 v[168:171], v226 offset:51200
	ds_read_b128 v[172:175], v226 offset:52224
	ds_read_b128 v[176:179], v226 offset:53248
	ds_read_b128 v[180:183], v226 offset:54272
	ds_read_b128 v[184:187], v226 offset:55296
	ds_read_b128 v[204:207], v226 offset:56320
	global_load_lds_dwordx4 v[208:209], off
	s_add_i32 m0, s20, 0x2000
	s_add_u32 s18, s18, 0x80080
	v_lshl_add_u64 v[208:209], v[210:211], 0, s[78:79]
	s_addc_u32 s19, s19, 0
	s_add_i32 s20, s70, s28
	global_load_lds_dwordx4 v[208:209], off
	v_lshl_add_u64 v[208:209], s[18:19], 0, v[200:201]
	s_mov_b32 m0, s20
	s_nop 0
	global_load_lds_dwordx4 v[208:209], off
	v_lshl_add_u64 v[208:209], s[18:19], 0, v[192:193]
	s_add_i32 m0, s20, 0x2000
	s_nop 0
	global_load_lds_dwordx4 v[208:209], off
	v_lshl_add_u64 v[208:209], v[212:213], 0, s[78:79]
	s_mov_b32 m0, s35
	s_nop 0
	global_load_lds_dwordx4 v[208:209], off
	v_lshl_add_u64 v[208:209], v[214:215], 0, s[78:79]
	s_mov_b32 m0, s38
	s_nop 0
	global_load_lds_dwordx4 v[208:209], off
	s_waitcnt vmcnt(8)
	s_waitcnt lgkmcnt(0)
	s_barrier
	s_setprio 1
	v_mfma_f32_16x16x32_bf16 v[60:63], v[112:115], v[160:163], v[60:63]
	v_mfma_f32_16x16x32_bf16 v[56:59], v[120:123], v[160:163], v[56:59]
	v_mfma_f32_16x16x32_bf16 v[44:47], v[112:115], v[168:171], v[44:47]
	v_mfma_f32_16x16x32_bf16 v[40:43], v[120:123], v[168:171], v[40:43]
	v_mfma_f32_16x16x32_bf16 v[28:31], v[112:115], v[176:179], v[28:31]
	v_mfma_f32_16x16x32_bf16 v[24:27], v[120:123], v[176:179], v[24:27]
	v_mfma_f32_16x16x32_bf16 v[12:15], v[112:115], v[184:187], v[12:15]
	v_mfma_f32_16x16x32_bf16 v[8:11], v[120:123], v[184:187], v[8:11]
	v_mfma_f32_16x16x32_bf16 v[60:63], v[116:119], v[164:167], v[60:63]
	v_mfma_f32_16x16x32_bf16 v[56:59], v[128:131], v[164:167], v[56:59]
	v_mfma_f32_16x16x32_bf16 v[44:47], v[116:119], v[172:175], v[44:47]
	v_mfma_f32_16x16x32_bf16 v[40:43], v[128:131], v[172:175], v[40:43]
	v_mfma_f32_16x16x32_bf16 v[28:31], v[116:119], v[180:183], v[28:31]
	v_mfma_f32_16x16x32_bf16 v[24:27], v[128:131], v[180:183], v[24:27]
	v_mfma_f32_16x16x32_bf16 v[12:15], v[116:119], v[204:207], v[12:15]
	v_mfma_f32_16x16x32_bf16 v[8:11], v[128:131], v[204:207], v[8:11]
	v_mfma_f32_16x16x32_bf16 v[52:55], v[136:139], v[160:163], v[52:55]
	v_mfma_f32_16x16x32_bf16 v[48:51], v[144:147], v[160:163], v[48:51]
	v_mfma_f32_16x16x32_bf16 v[36:39], v[136:139], v[168:171], v[36:39]
	v_mfma_f32_16x16x32_bf16 v[32:35], v[144:147], v[168:171], v[32:35]
	v_mfma_f32_16x16x32_bf16 v[20:23], v[136:139], v[176:179], v[20:23]
	v_mfma_f32_16x16x32_bf16 v[16:19], v[144:147], v[176:179], v[16:19]
	v_mfma_f32_16x16x32_bf16 v[4:7], v[136:139], v[184:187], v[4:7]
	v_mfma_f32_16x16x32_bf16 v[0:3], v[144:147], v[184:187], v[0:3]
	v_mfma_f32_16x16x32_bf16 v[52:55], v[140:143], v[164:167], v[52:55]
	v_mfma_f32_16x16x32_bf16 v[48:51], v[156:159], v[164:167], v[48:51]
	v_mfma_f32_16x16x32_bf16 v[36:39], v[140:143], v[172:175], v[36:39]
	v_mfma_f32_16x16x32_bf16 v[32:35], v[156:159], v[172:175], v[32:35]
	v_mfma_f32_16x16x32_bf16 v[20:23], v[140:143], v[180:183], v[20:23]
	v_mfma_f32_16x16x32_bf16 v[16:19], v[156:159], v[180:183], v[16:19]
	v_mfma_f32_16x16x32_bf16 v[4:7], v[140:143], v[204:207], v[4:7]
	v_mfma_f32_16x16x32_bf16 v[0:3], v[156:159], v[204:207], v[0:3]
	s_setprio 0
	s_barrier
	s_add_i32 s53, s53, 2
	s_add_u32 s45, s45, 0x100
	s_addc_u32 s52, s52, 0
	s_add_u32 s16, s16, 0x100
	s_addc_u32 s17, s17, 0
	s_cmp_gt_u32 s53, 29
	s_cbranch_scc0 .LBB0_682
	s_and_b64 vcc, exec, s[8:9]
	s_cbranch_vccz .LBB0_685
	s_barrier

; #define PG8_STAGE(bufoff, gbase, voff) do { _Pragma("unroll") for (int _i = 0; _i < 2; ++_i) \
;         __builtin_amdgcn_global_load_lds((const unsigned*)((const char*)(gbase) + (voff)[_i]), (LAS unsigned*)(lds + (bufoff) + ldsw + _i * 8192), 16, 0, 0); } while (0)
; #define PG8_LDA(dst, b, h) do { _Pragma("unroll") for (int m = 0; m < 4; ++m) _Pragma("unroll") for (int k = 0; k < 2; ++k) dst[m][k] = *(const LAS bf16x8*)(lds + PG8_SA(b, h) + aoff + m * 2048 + k * 1024); } while (0)
; #define PG8_LDB(dst, b, h) do { _Pragma("unroll") for (int n = 0; n < 2; ++n) _Pragma("unroll") for (int k = 0; k < 2; ++k) dst[n][k] = *(const LAS bf16x8*)(lds + PG8_SB(b, h) + boff + n * 2048 + k * 1024); } while (0)
; #define PG8_MMA(ai, bj, At, Bt) do { __builtin_amdgcn_s_setprio(1); _Pragma("unroll") for (int m = 0; m < 4; ++m) _Pragma("unroll") for (int n = 0; n < 2; ++n) _Pragma("unroll") for (int k = 0; k < 2; ++k) \
;         acc[ai][bj][m][n] = __builtin_amdgcn_mfma_f32_16x16x32_bf16(Bt[n][k], At[m][k], acc[ai][bj][m][n], 0, 0, 0); __builtin_amdgcn_s_setprio(0); } while (0)
; #define PG8_WAIT_V(n) asm volatile("s_waitcnt vmcnt(" #n ")" ::: "memory")
; #define PG8_WAIT_L(n) asm volatile("s_waitcnt lgkmcnt(" #n ")" ::: "memory")
; #define PG8_BAR __builtin_amdgcn_s_barrier()
; template <class Epi, class Sched, bool APERM = false, bool HALFN = false>
; __device__ __forceinline__ void gemm_phase(LAS unsigned char* lds, const int tid_in, const int K, const Sched& S, const Epi& E) {
;     ...
;             const bool last = (t == nt - 2);
;             const char* a1 = cA + (size_t)(t + 1) * kstep;
;             const char* a2 = last ? nA : cA + (size_t)(t + 2) * kstep; const char* b2 = last ? nB : cB + (size_t)(t + 2) * kstep;
;             const char* a3 = a2 + kstep; const char* b3 = b2 + kstep;
;             PG8_LDB(B0, 0, 0); PG8_LDB(B1, 0, 1); PG8_SCHED; PG8_LDA(At, 0, 0); PG8_STAGE(PG8_SA(1, 1), a1 + hstepA, voffA);
;             PG8_WAIT_V(8); PG8_WAIT_L(0); PG8_BAR; PG8_MMA(0, 0, At, B0); if constexpr (!HALFN) PG8_MMA(0, 1, At, B1); PG8_BAR; PG8_SCHED;
;             PG8_LDA(At, 0, 1); PG8_STAGE(PG8_SB(0, 0), b2, voffB); PG8_STAGE(PG8_SB(0, 1), b2 + hstep, voffB); PG8_STAGE(PG8_SA(0, 0), a2, voffA);
;             PG8_WAIT_V(8); PG8_WAIT_L(0); PG8_BAR; PG8_MMA(1, 0, At, B0); if constexpr (!HALFN) PG8_MMA(1, 1, At, B1); PG8_BAR; PG8_SCHED;
.LBB0_766:
	s_add_u32 s20, s18, 0xfff80080
	s_addc_u32 s21, s19, -1
	s_add_i32 s87, 0, 0x10000
	v_add_u32_e32 v95, s87, v99
	ds_read_b128 v[102:105], v95
	ds_read_b128 v[106:109], v95 offset:1024
	ds_read_b128 v[110:113], v95 offset:2048
	ds_read_b128 v[114:117], v95 offset:3072
	v_readlane_b32 s22, v255, 56
	s_nop 1
	s_cmp_eq_u32 s86, s22
	s_cselect_b32 s23, s76, s21
	s_cselect_b32 s22, s77, s20
	s_cselect_b32 s21, s74, s81
	s_cselect_b32 s20, s75, s80
	v_lshl_add_u64 v[96:97], s[18:19], 0, v[92:93]
	s_add_i32 m0, s34, 0xc000
	ds_read_b128 v[118:121], v101
	ds_read_b128 v[122:125], v101 offset:1024
	ds_read_b128 v[126:129], v101 offset:2048
	ds_read_b128 v[130:133], v101 offset:3072
	ds_read_b128 v[134:137], v101 offset:4096
	ds_read_b128 v[138:141], v101 offset:5120
	ds_read_b128 v[142:145], v101 offset:6144
	ds_read_b128 v[148:151], v101 offset:7168
	global_load_lds_dwordx4 v[96:97], off
	v_lshl_add_u64 v[96:97], s[18:19], 0, v[90:91]
	s_add_i32 m0, s34, 0xe000
	s_nop 0
	global_load_lds_dwordx4 v[96:97], off
	s_waitcnt vmcnt(8)
	s_waitcnt lgkmcnt(0)
	s_barrier
	s_setprio 1
	v_mfma_f32_16x16x32_bf16 v[60:63], v[102:105], v[118:121], v[60:63]
	v_mfma_f32_16x16x32_bf16 v[56:59], v[110:113], v[118:121], v[56:59]
	v_mfma_f32_16x16x32_bf16 v[52:55], v[102:105], v[126:129], v[52:55]
	v_mfma_f32_16x16x32_bf16 v[48:51], v[110:113], v[126:129], v[48:51]
	v_mfma_f32_16x16x32_bf16 v[44:47], v[102:105], v[134:137], v[44:47]
	v_mfma_f32_16x16x32_bf16 v[40:43], v[110:113], v[134:137], v[40:43]
	v_mfma_f32_16x16x32_bf16 v[36:39], v[102:105], v[142:145], v[36:39]
	v_mfma_f32_16x16x32_bf16 v[32:35], v[110:113], v[142:145], v[32:35]
	v_mfma_f32_16x16x32_bf16 v[60:63], v[106:109], v[122:125], v[60:63]
	v_mfma_f32_16x16x32_bf16 v[56:59], v[114:117], v[122:125], v[56:59]
	v_mfma_f32_16x16x32_bf16 v[52:55], v[106:109], v[130:133], v[52:55]
	v_mfma_f32_16x16x32_bf16 v[48:51], v[114:117], v[130:133], v[48:51]
	v_mfma_f32_16x16x32_bf16 v[44:47], v[106:109], v[138:141], v[44:47]
	v_mfma_f32_16x16x32_bf16 v[40:43], v[114:117], v[138:141], v[40:43]
	v_mfma_f32_16x16x32_bf16 v[36:39], v[106:109], v[148:151], v[36:39]
	v_mfma_f32_16x16x32_bf16 v[32:35], v[114:117], v[148:151], v[32:35]
	s_setprio 0
	s_barrier
	s_add_i32 s87, s87, s27
	v_lshl_add_u64 v[96:97], s[20:21], 0, v[68:69]
	s_mov_b32 m0, s87
	ds_read_b128 v[118:121], v101 offset:16384
	ds_read_b128 v[122:125], v101 offset:17408
	ds_read_b128 v[126:129], v101 offset:18432
	ds_read_b128 v[130:133], v101 offset:19456
	ds_read_b128 v[134:137], v101 offset:20480
	ds_read_b128 v[138:141], v101 offset:21504
	ds_read_b128 v[142:145], v101 offset:22528
	ds_read_b128 v[148:151], v101 offset:23552
	global_load_lds_dwordx4 v[96:97], off
	s_add_i32 m0, s87, 0x2000
	s_add_u32 s92, s20, 0x80000
	v_lshl_add_u64 v[152:153], s[20:21], 0, v[64:65]
	s_addc_u32 s93, s21, 0
	global_load_lds_dwordx4 v[152:153], off
	v_lshl_add_u64 v[154:155], s[92:93], 0, v[68:69]
	s_mov_b32 m0, s35
	v_lshl_add_u64 v[156:157], s[22:23], 0, v[66:67]
	global_load_lds_dwordx4 v[154:155], off
	v_lshl_add_u64 v[154:155], s[92:93], 0, v[64:65]
	s_mov_b32 m0, s38
	s_nop 0
	global_load_lds_dwordx4 v[154:155], off
	v_lshl_add_u64 v[154:155], s[22:23], 0, v[70:71]
	s_mov_b32 m0, s34
	s_nop 0
	global_load_lds_dwordx4 v[154:155], off
	s_mov_b32 m0, s39
	s_nop 0
	global_load_lds_dwordx4 v[156:157], off
	s_waitcnt vmcnt(8)
	s_waitcnt lgkmcnt(0)
	s_barrier
	s_setprio 1
	v_mfma_f32_16x16x32_bf16 v[28:31], v[102:105], v[118:121], v[28:31]
	v_mfma_f32_16x16x32_bf16 v[24:27], v[110:113], v[118:121], v[24:27]
	v_mfma_f32_16x16x32_bf16 v[20:23], v[102:105], v[126:129], v[20:23]
	v_mfma_f32_16x16x32_bf16 v[16:19], v[110:113], v[126:129], v[16:19]
	v_mfma_f32_16x16x32_bf16 v[12:15], v[102:105], v[134:137], v[12:15]
	v_mfma_f32_16x16x32_bf16 v[8:11], v[110:113], v[134:137], v[8:11]
	v_mfma_f32_16x16x32_bf16 v[4:7], v[102:105], v[142:145], v[4:7]
	v_mfma_f32_16x16x32_bf16 v[0:3], v[110:113], v[142:145], v[0:3]
	v_mfma_f32_16x16x32_bf16 v[28:31], v[106:109], v[122:125], v[28:31]
	v_mfma_f32_16x16x32_bf16 v[24:27], v[114:117], v[122:125], v[24:27]
	v_mfma_f32_16x16x32_bf16 v[20:23], v[106:109], v[130:133], v[20:23]
	v_mfma_f32_16x16x32_bf16 v[16:19], v[114:117], v[130:133], v[16:19]
	v_mfma_f32_16x16x32_bf16 v[12:15], v[106:109], v[138:141], v[12:15]
	v_mfma_f32_16x16x32_bf16 v[8:11], v[114:117], v[138:141], v[8:11]
	v_mfma_f32_16x16x32_bf16 v[4:7], v[106:109], v[148:151], v[4:7]
	v_mfma_f32_16x16x32_bf16 v[0:3], v[114:117], v[148:151], v[0:3]
	s_setprio 0
	s_barrier
; #define PG8_STAGE(bufoff, gbase, voff) do { _Pragma("unroll") for (int _i = 0; _i < 2; ++_i) \
;         __builtin_amdgcn_global_load_lds((const unsigned*)((const char*)(gbase) + (voff)[_i]), (LAS unsigned*)(lds + (bufoff) + ldsw + _i * 8192), 16, 0, 0); } while (0)
; #define PG8_LDA(dst, b, h) do { _Pragma("unroll") for (int m = 0; m < 4; ++m) _Pragma("unroll") for (int k = 0; k < 2; ++k) dst[m][k] = *(const LAS bf16x8*)(lds + PG8_SA(b, h) + aoff + m * 2048 + k * 1024); } while (0)
; #define PG8_LDB(dst, b, h) do { _Pragma("unroll") for (int n = 0; n < 2; ++n) _Pragma("unroll") for (int k = 0; k < 2; ++k) dst[n][k] = *(const LAS bf16x8*)(lds + PG8_SB(b, h) + boff + n * 2048 + k * 1024); } while (0)
; #define PG8_MMA(ai, bj, At, Bt) do { __builtin_amdgcn_s_setprio(1); _Pragma("unroll") for (int m = 0; m < 4; ++m) _Pragma("unroll") for (int n = 0; n < 2; ++n) _Pragma("unroll") for (int k = 0; k < 2; ++k) \
;         acc[ai][bj][m][n] = __builtin_amdgcn_mfma_f32_16x16x32_bf16(Bt[n][k], At[m][k], acc[ai][bj][m][n], 0, 0, 0); __builtin_amdgcn_s_setprio(0); } while (0)
; #define PG8_WAIT_V(n) asm volatile("s_waitcnt vmcnt(" #n ")" ::: "memory")
; #define PG8_WAIT_L(n) asm volatile("s_waitcnt lgkmcnt(" #n ")" ::: "memory")
; #define PG8_BAR __builtin_amdgcn_s_barrier()
; #define PG8_SCHED __builtin_amdgcn_sched_barrier(0)
; template <class Epi, class Sched, bool APERM = false, bool HALFN = false>
; __device__ __forceinline__ void gemm_phase(LAS unsigned char* lds, const int tid_in, const int K, const Sched& S, const Epi& E) {
;     ...
;             PG8_LDB(B0, 1, 0); PG8_LDB(B1, 1, 1); PG8_SCHED; PG8_LDA(At, 1, 0); PG8_STAGE(PG8_SA(0, 1), a2 + hstepA, voffA);
;             PG8_WAIT_V(8); PG8_WAIT_L(0); PG8_BAR; PG8_MMA(0, 0, At, B0); if constexpr (!HALFN) PG8_MMA(0, 1, At, B1); PG8_BAR; PG8_SCHED;
;             PG8_LDA(At, 1, 1); PG8_STAGE(PG8_SB(1, 0), b3, voffB); PG8_STAGE(PG8_SB(1, 1), b3 + hstep, voffB); PG8_STAGE(PG8_SA(1, 0), a3, voffA);
;             PG8_WAIT_V(8); PG8_WAIT_L(0); PG8_BAR; PG8_MMA(1, 0, At, B0); if constexpr (!HALFN) PG8_MMA(1, 1, At, B1); PG8_BAR; PG8_SCHED;
;         }
;         if (wr == 0) PG8_BAR;
	s_add_i32 s87, 0, 0x18000
	v_add_u32_e32 v95, s87, v99
	ds_read_b128 v[102:105], v95
	ds_read_b128 v[106:109], v95 offset:1024
	ds_read_b128 v[110:113], v95 offset:2048
	ds_read_b128 v[114:117], v95 offset:3072
	s_add_u32 s22, s22, 0x80000
	s_addc_u32 s23, s23, 0
	s_mov_b32 m0, s44
	v_lshl_add_u64 v[158:159], s[22:23], 0, v[70:71]
	ds_read_b128 v[118:121], v101 offset:32768
	ds_read_b128 v[122:125], v101 offset:33792
	ds_read_b128 v[126:129], v101 offset:34816
	ds_read_b128 v[130:133], v101 offset:35840
	ds_read_b128 v[134:137], v101 offset:36864
	ds_read_b128 v[138:141], v101 offset:37888
	ds_read_b128 v[142:145], v101 offset:38912
	ds_read_b128 v[148:151], v101 offset:39936
	global_load_lds_dwordx4 v[158:159], off
	v_lshl_add_u64 v[158:159], s[22:23], 0, v[66:67]
	s_mov_b32 m0, s45
	s_nop 0
	global_load_lds_dwordx4 v[158:159], off
	s_waitcnt vmcnt(8)
	s_waitcnt lgkmcnt(0)
	s_barrier
	s_setprio 1
	v_mfma_f32_16x16x32_bf16 v[60:63], v[102:105], v[118:121], v[60:63]
	v_mfma_f32_16x16x32_bf16 v[56:59], v[110:113], v[118:121], v[56:59]
	v_mfma_f32_16x16x32_bf16 v[52:55], v[102:105], v[126:129], v[52:55]
	v_mfma_f32_16x16x32_bf16 v[48:51], v[110:113], v[126:129], v[48:51]
	v_mfma_f32_16x16x32_bf16 v[44:47], v[102:105], v[134:137], v[44:47]
	v_mfma_f32_16x16x32_bf16 v[40:43], v[110:113], v[134:137], v[40:43]
	v_mfma_f32_16x16x32_bf16 v[36:39], v[102:105], v[142:145], v[36:39]
	v_mfma_f32_16x16x32_bf16 v[32:35], v[110:113], v[142:145], v[32:35]
	v_mfma_f32_16x16x32_bf16 v[60:63], v[106:109], v[122:125], v[60:63]
	v_mfma_f32_16x16x32_bf16 v[56:59], v[114:117], v[122:125], v[56:59]
	v_mfma_f32_16x16x32_bf16 v[52:55], v[106:109], v[130:133], v[52:55]
	v_mfma_f32_16x16x32_bf16 v[48:51], v[114:117], v[130:133], v[48:51]
	v_mfma_f32_16x16x32_bf16 v[44:47], v[106:109], v[138:141], v[44:47]
	v_mfma_f32_16x16x32_bf16 v[40:43], v[114:117], v[138:141], v[40:43]
	v_mfma_f32_16x16x32_bf16 v[36:39], v[106:109], v[148:151], v[36:39]
	v_mfma_f32_16x16x32_bf16 v[32:35], v[114:117], v[148:151], v[32:35]
	s_setprio 0
	s_barrier
	s_add_i32 s22, s87, s27
	v_lshl_add_u64 v[96:97], v[96:97], 0, s[78:79]
	s_mov_b32 m0, s22
	ds_read_b128 v[118:121], v101 offset:49152
	ds_read_b128 v[122:125], v101 offset:50176
	ds_read_b128 v[126:129], v101 offset:51200
	ds_read_b128 v[130:133], v101 offset:52224
	ds_read_b128 v[134:137], v101 offset:53248
	ds_read_b128 v[138:141], v101 offset:54272
	ds_read_b128 v[142:145], v101 offset:55296
	ds_read_b128 v[148:151], v101 offset:56320
	global_load_lds_dwordx4 v[96:97], off
	s_add_i32 m0, s22, 0x2000
	s_add_u32 s20, s20, 0x80080
	v_lshl_add_u64 v[96:97], v[152:153], 0, s[78:79]
	s_addc_u32 s21, s21, 0
	global_load_lds_dwordx4 v[96:97], off
	v_lshl_add_u64 v[96:97], s[20:21], 0, v[68:69]
	s_mov_b32 m0, s57
	s_nop 0
	global_load_lds_dwordx4 v[96:97], off
	v_lshl_add_u64 v[96:97], s[20:21], 0, v[64:65]
	s_mov_b32 m0, s70
	s_nop 0
	global_load_lds_dwordx4 v[96:97], off
	v_lshl_add_u64 v[96:97], v[154:155], 0, s[78:79]
	s_mov_b32 m0, s52
	s_nop 0
	global_load_lds_dwordx4 v[96:97], off
	v_lshl_add_u64 v[96:97], v[156:157], 0, s[78:79]
	s_mov_b32 m0, s53
	s_nop 0
	global_load_lds_dwordx4 v[96:97], off
	s_waitcnt vmcnt(8)
	s_waitcnt lgkmcnt(0)
	s_barrier
	s_setprio 1
	v_mfma_f32_16x16x32_bf16 v[28:31], v[102:105], v[118:121], v[28:31]
	v_mfma_f32_16x16x32_bf16 v[24:27], v[110:113], v[118:121], v[24:27]
	v_mfma_f32_16x16x32_bf16 v[20:23], v[102:105], v[126:129], v[20:23]
	v_mfma_f32_16x16x32_bf16 v[16:19], v[110:113], v[126:129], v[16:19]
	v_mfma_f32_16x16x32_bf16 v[12:15], v[102:105], v[134:137], v[12:15]
	v_mfma_f32_16x16x32_bf16 v[8:11], v[110:113], v[134:137], v[8:11]
	v_mfma_f32_16x16x32_bf16 v[4:7], v[102:105], v[142:145], v[4:7]
	v_mfma_f32_16x16x32_bf16 v[0:3], v[110:113], v[142:145], v[0:3]
	v_mfma_f32_16x16x32_bf16 v[28:31], v[106:109], v[122:125], v[28:31]
	v_mfma_f32_16x16x32_bf16 v[24:27], v[114:117], v[122:125], v[24:27]
	v_mfma_f32_16x16x32_bf16 v[20:23], v[106:109], v[130:133], v[20:23]
	v_mfma_f32_16x16x32_bf16 v[16:19], v[114:117], v[130:133], v[16:19]
	v_mfma_f32_16x16x32_bf16 v[12:15], v[106:109], v[138:141], v[12:15]
	v_mfma_f32_16x16x32_bf16 v[8:11], v[114:117], v[138:141], v[8:11]
	v_mfma_f32_16x16x32_bf16 v[4:7], v[106:109], v[148:151], v[4:7]
	v_mfma_f32_16x16x32_bf16 v[0:3], v[114:117], v[148:151], v[0:3]
	s_setprio 0
	s_barrier
	s_add_i32 s86, s86, 2
	s_add_u32 s80, s80, 0x100
	s_addc_u32 s81, s81, 0
	s_add_u32 s18, s18, 0x100
	s_addc_u32 s19, s19, 0
	v_readlane_b32 s20, v255, 55
	s_nop 1
	s_cmp_gt_u32 s86, s20
	s_cbranch_scc0 .LBB0_766
	s_and_b64 vcc, exec, s[12:13]
	s_cbranch_vccz .LBB0_769
	s_barrier

; #define PG8_STAGE(bufoff, gbase, voff) do { _Pragma("unroll") for (int _i = 0; _i < 2; ++_i) \
;         __builtin_amdgcn_global_load_lds((const unsigned*)((const char*)(gbase) + (voff)[_i]), (LAS unsigned*)(lds + (bufoff) + ldsw + _i * 8192), 16, 0, 0); } while (0)
; #define PG8_LDA(dst, b, h) do { _Pragma("unroll") for (int m = 0; m < 4; ++m) _Pragma("unroll") for (int k = 0; k < 2; ++k) dst[m][k] = *(const LAS bf16x8*)(lds + PG8_SA(b, h) + aoff + m * 2048 + k * 1024); } while (0)
; #define PG8_LDB(dst, b, h) do { _Pragma("unroll") for (int n = 0; n < 2; ++n) _Pragma("unroll") for (int k = 0; k < 2; ++k) dst[n][k] = *(const LAS bf16x8*)(lds + PG8_SB(b, h) + boff + n * 2048 + k * 1024); } while (0)
; #define PG8_MMA(ai, bj, At, Bt) do { __builtin_amdgcn_s_setprio(1); _Pragma("unroll") for (int m = 0; m < 4; ++m) _Pragma("unroll") for (int n = 0; n < 2; ++n) _Pragma("unroll") for (int k = 0; k < 2; ++k) \
;         acc[ai][bj][m][n] = __builtin_amdgcn_mfma_f32_16x16x32_bf16(Bt[n][k], At[m][k], acc[ai][bj][m][n], 0, 0, 0); __builtin_amdgcn_s_setprio(0); } while (0)
; #define PG8_WAIT_V(n) asm volatile("s_waitcnt vmcnt(" #n ")" ::: "memory")
; #define PG8_WAIT_L(n) asm volatile("s_waitcnt lgkmcnt(" #n ")" ::: "memory")
; #define PG8_BAR __builtin_amdgcn_s_barrier()
; template <class Epi, class Sched, bool APERM = false, bool HALFN = false>
; __device__ __forceinline__ void gemm_phase(LAS unsigned char* lds, const int tid_in, const int K, const Sched& S, const Epi& E) {
;     ...
;             const bool last = (t == nt - 2);
;             const char* a1 = cA + (size_t)(t + 1) * kstep;
;             const char* a2 = last ? nA : cA + (size_t)(t + 2) * kstep; const char* b2 = last ? nB : cB + (size_t)(t + 2) * kstep;
;             const char* a3 = a2 + kstep; const char* b3 = b2 + kstep;
;             PG8_LDB(B0, 0, 0); PG8_LDB(B1, 0, 1); PG8_SCHED; PG8_LDA(At, 0, 0); PG8_STAGE(PG8_SA(1, 1), a1 + hstepA, voffA);
;             PG8_WAIT_V(8); PG8_WAIT_L(0); PG8_BAR; PG8_MMA(0, 0, At, B0); if constexpr (!HALFN) PG8_MMA(0, 1, At, B1); PG8_BAR; PG8_SCHED;
;             PG8_LDA(At, 0, 1); PG8_STAGE(PG8_SB(0, 0), b2, voffB); PG8_STAGE(PG8_SB(0, 1), b2 + hstep, voffB); PG8_STAGE(PG8_SA(0, 0), a2, voffA);
;             PG8_WAIT_V(8); PG8_WAIT_L(0); PG8_BAR; PG8_MMA(1, 0, At, B0); if constexpr (!HALFN) PG8_MMA(1, 1, At, B1); PG8_BAR; PG8_SCHED;
.LBB0_806:
	s_add_u32 s18, s16, 0xfffe0080
	s_addc_u32 s19, s17, -1
	s_add_i32 s57, 0, 0x10000
	s_cmp_eq_u32 s53, 4
	s_cselect_b32 s21, s11, s19
	s_cselect_b32 s20, s10, s18
	s_cselect_b32 s19, s13, s52
	s_cselect_b32 s18, s12, s45
	s_add_i32 s72, 0, 0x14000
	v_add_u32_e32 v128, s57, v220
	v_add_u32_e32 v156, s72, v220
	ds_read_b128 v[112:115], v128
	ds_read_b128 v[116:119], v128 offset:1024
	ds_read_b128 v[120:123], v128 offset:2048
	ds_read_b128 v[128:131], v128 offset:3072
	ds_read_b128 v[136:139], v156
	ds_read_b128 v[140:143], v156 offset:1024
	ds_read_b128 v[144:147], v156 offset:2048
	ds_read_b128 v[156:159], v156 offset:3072
	v_lshl_add_u64 v[208:209], s[16:17], 0, v[198:199]
	s_add_i32 m0, s29, 0xc000
	ds_read_b128 v[160:163], v226
	ds_read_b128 v[164:167], v226 offset:1024
	ds_read_b128 v[168:171], v226 offset:2048
	ds_read_b128 v[172:175], v226 offset:3072
	ds_read_b128 v[176:179], v226 offset:4096
	ds_read_b128 v[180:183], v226 offset:5120
	ds_read_b128 v[184:187], v226 offset:6144
	ds_read_b128 v[204:207], v226 offset:7168
	global_load_lds_dwordx4 v[208:209], off
	v_lshl_add_u64 v[208:209], s[16:17], 0, v[196:197]
	s_add_i32 m0, s29, 0xe000
	s_nop 0
	global_load_lds_dwordx4 v[208:209], off
	s_waitcnt vmcnt(8)
	s_waitcnt lgkmcnt(0)
	s_barrier
	s_setprio 1
	v_mfma_f32_16x16x32_bf16 v[152:155], v[112:115], v[160:163], v[152:155]
	v_mfma_f32_16x16x32_bf16 v[148:151], v[120:123], v[160:163], v[148:151]
	v_mfma_f32_16x16x32_bf16 v[108:111], v[112:115], v[168:171], v[108:111]
	v_mfma_f32_16x16x32_bf16 v[104:107], v[120:123], v[168:171], v[104:107]
	v_mfma_f32_16x16x32_bf16 v[92:95], v[112:115], v[176:179], v[92:95]
	v_mfma_f32_16x16x32_bf16 v[88:91], v[120:123], v[176:179], v[88:91]
	v_mfma_f32_16x16x32_bf16 v[76:79], v[112:115], v[184:187], v[76:79]
	v_mfma_f32_16x16x32_bf16 v[72:75], v[120:123], v[184:187], v[72:75]
	v_mfma_f32_16x16x32_bf16 v[152:155], v[116:119], v[164:167], v[152:155]
	v_mfma_f32_16x16x32_bf16 v[148:151], v[128:131], v[164:167], v[148:151]
	v_mfma_f32_16x16x32_bf16 v[108:111], v[116:119], v[172:175], v[108:111]
	v_mfma_f32_16x16x32_bf16 v[104:107], v[128:131], v[172:175], v[104:107]
	v_mfma_f32_16x16x32_bf16 v[92:95], v[116:119], v[180:183], v[92:95]
	v_mfma_f32_16x16x32_bf16 v[88:91], v[128:131], v[180:183], v[88:91]
	v_mfma_f32_16x16x32_bf16 v[76:79], v[116:119], v[204:207], v[76:79]
	v_mfma_f32_16x16x32_bf16 v[72:75], v[128:131], v[204:207], v[72:75]
	v_mfma_f32_16x16x32_bf16 v[132:135], v[136:139], v[160:163], v[132:135]
	v_mfma_f32_16x16x32_bf16 v[124:127], v[144:147], v[160:163], v[124:127]
	v_mfma_f32_16x16x32_bf16 v[100:103], v[136:139], v[168:171], v[100:103]
	v_mfma_f32_16x16x32_bf16 v[96:99], v[144:147], v[168:171], v[96:99]
	v_mfma_f32_16x16x32_bf16 v[84:87], v[136:139], v[176:179], v[84:87]
	v_mfma_f32_16x16x32_bf16 v[80:83], v[144:147], v[176:179], v[80:83]
	v_mfma_f32_16x16x32_bf16 v[68:71], v[136:139], v[184:187], v[68:71]
	v_mfma_f32_16x16x32_bf16 v[64:67], v[144:147], v[184:187], v[64:67]
	v_mfma_f32_16x16x32_bf16 v[132:135], v[140:143], v[164:167], v[132:135]
	v_mfma_f32_16x16x32_bf16 v[124:127], v[156:159], v[164:167], v[124:127]
	v_mfma_f32_16x16x32_bf16 v[100:103], v[140:143], v[172:175], v[100:103]
	v_mfma_f32_16x16x32_bf16 v[96:99], v[156:159], v[172:175], v[96:99]
	v_mfma_f32_16x16x32_bf16 v[84:87], v[140:143], v[180:183], v[84:87]
	v_mfma_f32_16x16x32_bf16 v[80:83], v[156:159], v[180:183], v[80:83]
	v_mfma_f32_16x16x32_bf16 v[68:71], v[140:143], v[204:207], v[68:71]
	v_mfma_f32_16x16x32_bf16 v[64:67], v[156:159], v[204:207], v[64:67]
	s_setprio 0
	s_barrier
	s_add_i32 s57, s57, s28
	v_lshl_add_u64 v[208:209], s[18:19], 0, v[200:201]
	s_mov_b32 m0, s57
	ds_read_b128 v[160:163], v226 offset:16384
	ds_read_b128 v[164:167], v226 offset:17408
	ds_read_b128 v[168:171], v226 offset:18432
	ds_read_b128 v[172:175], v226 offset:19456
	ds_read_b128 v[176:179], v226 offset:20480
	ds_read_b128 v[180:183], v226 offset:21504
	ds_read_b128 v[184:187], v226 offset:22528
	ds_read_b128 v[204:207], v226 offset:23552
	global_load_lds_dwordx4 v[208:209], off
	s_add_i32 m0, s57, 0x2000
	s_add_u32 s70, s18, 0x20000
	v_lshl_add_u64 v[210:211], s[18:19], 0, v[192:193]
	s_addc_u32 s71, s19, 0
	s_add_i32 s57, s72, s28
	global_load_lds_dwordx4 v[210:211], off
	v_lshl_add_u64 v[212:213], s[70:71], 0, v[200:201]
	s_mov_b32 m0, s57
	v_lshl_add_u64 v[214:215], s[20:21], 0, v[190:191]
	global_load_lds_dwordx4 v[212:213], off
	v_lshl_add_u64 v[212:213], s[70:71], 0, v[192:193]
	s_add_i32 m0, s57, 0x2000
	s_nop 0
	global_load_lds_dwordx4 v[212:213], off
	v_lshl_add_u64 v[212:213], s[20:21], 0, v[188:189]
	s_mov_b32 m0, s29
	s_nop 0
	global_load_lds_dwordx4 v[212:213], off
	s_mov_b32 m0, s30
	s_nop 0
	global_load_lds_dwordx4 v[214:215], off
	s_waitcnt vmcnt(8)
	s_waitcnt lgkmcnt(0)
	s_barrier
; #define PG8_STAGE(bufoff, gbase, voff) do { _Pragma("unroll") for (int _i = 0; _i < 2; ++_i) \
;         __builtin_amdgcn_global_load_lds((const unsigned*)((const char*)(gbase) + (voff)[_i]), (LAS unsigned*)(lds + (bufoff) + ldsw + _i * 8192), 16, 0, 0); } while (0)
; #define PG8_LDA(dst, b, h) do { _Pragma("unroll") for (int m = 0; m < 4; ++m) _Pragma("unroll") for (int k = 0; k < 2; ++k) dst[m][k] = *(const LAS bf16x8*)(lds + PG8_SA(b, h) + aoff + m * 2048 + k * 1024); } while (0)
; #define PG8_LDB(dst, b, h) do { _Pragma("unroll") for (int n = 0; n < 2; ++n) _Pragma("unroll") for (int k = 0; k < 2; ++k) dst[n][k] = *(const LAS bf16x8*)(lds + PG8_SB(b, h) + boff + n * 2048 + k * 1024); } while (0)
; #define PG8_MMA(ai, bj, At, Bt) do { __builtin_amdgcn_s_setprio(1); _Pragma("unroll") for (int m = 0; m < 4; ++m) _Pragma("unroll") for (int n = 0; n < 2; ++n) _Pragma("unroll") for (int k = 0; k < 2; ++k) \
;         acc[ai][bj][m][n] = __builtin_amdgcn_mfma_f32_16x16x32_bf16(Bt[n][k], At[m][k], acc[ai][bj][m][n], 0, 0, 0); __builtin_amdgcn_s_setprio(0); } while (0)
; #define PG8_WAIT_V(n) asm volatile("s_waitcnt vmcnt(" #n ")" ::: "memory")
; #define PG8_WAIT_L(n) asm volatile("s_waitcnt lgkmcnt(" #n ")" ::: "memory")
; #define PG8_BAR __builtin_amdgcn_s_barrier()
; #define PG8_SCHED __builtin_amdgcn_sched_barrier(0)
; template <class Epi, class Sched, bool APERM = false, bool HALFN = false>
; __device__ __forceinline__ void gemm_phase(LAS unsigned char* lds, const int tid_in, const int K, const Sched& S, const Epi& E) {
;     ...
;             PG8_WAIT_V(8); PG8_WAIT_L(0); PG8_BAR; PG8_MMA(1, 0, At, B0); if constexpr (!HALFN) PG8_MMA(1, 1, At, B1); PG8_BAR; PG8_SCHED;
;             PG8_LDB(B0, 1, 0); PG8_LDB(B1, 1, 1); PG8_SCHED; PG8_LDA(At, 1, 0); PG8_STAGE(PG8_SA(0, 1), a2 + hstepA, voffA);
;             PG8_WAIT_V(8); PG8_WAIT_L(0); PG8_BAR; PG8_MMA(0, 0, At, B0); if constexpr (!HALFN) PG8_MMA(0, 1, At, B1); PG8_BAR; PG8_SCHED;
	s_setprio 1
	v_mfma_f32_16x16x32_bf16 v[60:63], v[112:115], v[160:163], v[60:63]
	v_mfma_f32_16x16x32_bf16 v[56:59], v[120:123], v[160:163], v[56:59]
	v_mfma_f32_16x16x32_bf16 v[44:47], v[112:115], v[168:171], v[44:47]
	v_mfma_f32_16x16x32_bf16 v[40:43], v[120:123], v[168:171], v[40:43]
	v_mfma_f32_16x16x32_bf16 v[28:31], v[112:115], v[176:179], v[28:31]
	v_mfma_f32_16x16x32_bf16 v[24:27], v[120:123], v[176:179], v[24:27]
	v_mfma_f32_16x16x32_bf16 v[12:15], v[112:115], v[184:187], v[12:15]
	v_mfma_f32_16x16x32_bf16 v[8:11], v[120:123], v[184:187], v[8:11]
	v_mfma_f32_16x16x32_bf16 v[60:63], v[116:119], v[164:167], v[60:63]
	v_mfma_f32_16x16x32_bf16 v[56:59], v[128:131], v[164:167], v[56:59]
	v_mfma_f32_16x16x32_bf16 v[44:47], v[116:119], v[172:175], v[44:47]
	v_mfma_f32_16x16x32_bf16 v[40:43], v[128:131], v[172:175], v[40:43]
	v_mfma_f32_16x16x32_bf16 v[28:31], v[116:119], v[180:183], v[28:31]
	v_mfma_f32_16x16x32_bf16 v[24:27], v[128:131], v[180:183], v[24:27]
	v_mfma_f32_16x16x32_bf16 v[12:15], v[116:119], v[204:207], v[12:15]
	v_mfma_f32_16x16x32_bf16 v[8:11], v[128:131], v[204:207], v[8:11]
	v_mfma_f32_16x16x32_bf16 v[52:55], v[136:139], v[160:163], v[52:55]
	v_mfma_f32_16x16x32_bf16 v[48:51], v[144:147], v[160:163], v[48:51]
	v_mfma_f32_16x16x32_bf16 v[36:39], v[136:139], v[168:171], v[36:39]
	v_mfma_f32_16x16x32_bf16 v[32:35], v[144:147], v[168:171], v[32:35]
	v_mfma_f32_16x16x32_bf16 v[20:23], v[136:139], v[176:179], v[20:23]
	v_mfma_f32_16x16x32_bf16 v[16:19], v[144:147], v[176:179], v[16:19]
	v_mfma_f32_16x16x32_bf16 v[4:7], v[136:139], v[184:187], v[4:7]
	v_mfma_f32_16x16x32_bf16 v[0:3], v[144:147], v[184:187], v[0:3]
	v_mfma_f32_16x16x32_bf16 v[52:55], v[140:143], v[164:167], v[52:55]
	v_mfma_f32_16x16x32_bf16 v[48:51], v[156:159], v[164:167], v[48:51]
	v_mfma_f32_16x16x32_bf16 v[36:39], v[140:143], v[172:175], v[36:39]
	v_mfma_f32_16x16x32_bf16 v[32:35], v[156:159], v[172:175], v[32:35]
	v_mfma_f32_16x16x32_bf16 v[20:23], v[140:143], v[180:183], v[20:23]
	v_mfma_f32_16x16x32_bf16 v[16:19], v[156:159], v[180:183], v[16:19]
	v_mfma_f32_16x16x32_bf16 v[4:7], v[140:143], v[204:207], v[4:7]
	v_mfma_f32_16x16x32_bf16 v[0:3], v[156:159], v[204:207], v[0:3]
	s_setprio 0
	s_barrier
	s_add_i32 s57, 0, 0x18000
	s_add_i32 s70, 0, 0x1c000
	v_add_u32_e32 v128, s57, v220
	v_add_u32_e32 v156, s70, v220
	ds_read_b128 v[112:115], v128
	ds_read_b128 v[116:119], v128 offset:1024
	ds_read_b128 v[120:123], v128 offset:2048
	ds_read_b128 v[128:131], v128 offset:3072
	ds_read_b128 v[136:139], v156
	ds_read_b128 v[140:143], v156 offset:1024
	ds_read_b128 v[144:147], v156 offset:2048
	ds_read_b128 v[156:159], v156 offset:3072
	s_add_u32 s20, s20, 0x20000
	s_addc_u32 s21, s21, 0
	s_mov_b32 m0, s31
	v_lshl_add_u64 v[216:217], s[20:21], 0, v[188:189]
	ds_read_b128 v[160:163], v226 offset:32768
	ds_read_b128 v[164:167], v226 offset:33792
	ds_read_b128 v[168:171], v226 offset:34816
	ds_read_b128 v[172:175], v226 offset:35840
	ds_read_b128 v[176:179], v226 offset:36864
	ds_read_b128 v[180:183], v226 offset:37888
	ds_read_b128 v[184:187], v226 offset:38912
	ds_read_b128 v[204:207], v226 offset:39936
	global_load_lds_dwordx4 v[216:217], off
	v_lshl_add_u64 v[216:217], s[20:21], 0, v[190:191]
	s_mov_b32 m0, s34
	s_nop 0
	global_load_lds_dwordx4 v[216:217], off
	s_waitcnt vmcnt(8)
	s_waitcnt lgkmcnt(0)
	s_barrier
	s_setprio 1
	v_mfma_f32_16x16x32_bf16 v[152:155], v[112:115], v[160:163], v[152:155]
	v_mfma_f32_16x16x32_bf16 v[148:151], v[120:123], v[160:163], v[148:151]
	v_mfma_f32_16x16x32_bf16 v[108:111], v[112:115], v[168:171], v[108:111]
	v_mfma_f32_16x16x32_bf16 v[104:107], v[120:123], v[168:171], v[104:107]
	v_mfma_f32_16x16x32_bf16 v[92:95], v[112:115], v[176:179], v[92:95]
	v_mfma_f32_16x16x32_bf16 v[88:91], v[120:123], v[176:179], v[88:91]
	v_mfma_f32_16x16x32_bf16 v[76:79], v[112:115], v[184:187], v[76:79]
	v_mfma_f32_16x16x32_bf16 v[72:75], v[120:123], v[184:187], v[72:75]
	v_mfma_f32_16x16x32_bf16 v[152:155], v[116:119], v[164:167], v[152:155]
	v_mfma_f32_16x16x32_bf16 v[148:151], v[128:131], v[164:167], v[148:151]
	v_mfma_f32_16x16x32_bf16 v[108:111], v[116:119], v[172:175], v[108:111]
	v_mfma_f32_16x16x32_bf16 v[104:107], v[128:131], v[172:175], v[104:107]
	v_mfma_f32_16x16x32_bf16 v[92:95], v[116:119], v[180:183], v[92:95]
	v_mfma_f32_16x16x32_bf16 v[88:91], v[128:131], v[180:183], v[88:91]
	v_mfma_f32_16x16x32_bf16 v[76:79], v[116:119], v[204:207], v[76:79]
	v_mfma_f32_16x16x32_bf16 v[72:75], v[128:131], v[204:207], v[72:75]
	v_mfma_f32_16x16x32_bf16 v[132:135], v[136:139], v[160:163], v[132:135]
	v_mfma_f32_16x16x32_bf16 v[124:127], v[144:147], v[160:163], v[124:127]
	v_mfma_f32_16x16x32_bf16 v[100:103], v[136:139], v[168:171], v[100:103]
	v_mfma_f32_16x16x32_bf16 v[96:99], v[144:147], v[168:171], v[96:99]
	v_mfma_f32_16x16x32_bf16 v[84:87], v[136:139], v[176:179], v[84:87]
	v_mfma_f32_16x16x32_bf16 v[80:83], v[144:147], v[176:179], v[80:83]
	v_mfma_f32_16x16x32_bf16 v[68:71], v[136:139], v[184:187], v[68:71]
	v_mfma_f32_16x16x32_bf16 v[64:67], v[144:147], v[184:187], v[64:67]
	v_mfma_f32_16x16x32_bf16 v[132:135], v[140:143], v[164:167], v[132:135]
	v_mfma_f32_16x16x32_bf16 v[124:127], v[156:159], v[164:167], v[124:127]
	v_mfma_f32_16x16x32_bf16 v[100:103], v[140:143], v[172:175], v[100:103]
	v_mfma_f32_16x16x32_bf16 v[96:99], v[156:159], v[172:175], v[96:99]
	v_mfma_f32_16x16x32_bf16 v[84:87], v[140:143], v[180:183], v[84:87]
	v_mfma_f32_16x16x32_bf16 v[80:83], v[156:159], v[180:183], v[80:83]
	v_mfma_f32_16x16x32_bf16 v[68:71], v[140:143], v[204:207], v[68:71]
	v_mfma_f32_16x16x32_bf16 v[64:67], v[156:159], v[204:207], v[64:67]
	s_setprio 0
	s_barrier
; #define PG8_STAGE(bufoff, gbase, voff) do { _Pragma("unroll") for (int _i = 0; _i < 2; ++_i) \
;         __builtin_amdgcn_global_load_lds((const unsigned*)((const char*)(gbase) + (voff)[_i]), (LAS unsigned*)(lds + (bufoff) + ldsw + _i * 8192), 16, 0, 0); } while (0)
; #define PG8_LDA(dst, b, h) do { _Pragma("unroll") for (int m = 0; m < 4; ++m) _Pragma("unroll") for (int k = 0; k < 2; ++k) dst[m][k] = *(const LAS bf16x8*)(lds + PG8_SA(b, h) + aoff + m * 2048 + k * 1024); } while (0)
; #define PG8_MMA(ai, bj, At, Bt) do { __builtin_amdgcn_s_setprio(1); _Pragma("unroll") for (int m = 0; m < 4; ++m) _Pragma("unroll") for (int n = 0; n < 2; ++n) _Pragma("unroll") for (int k = 0; k < 2; ++k) \
;         acc[ai][bj][m][n] = __builtin_amdgcn_mfma_f32_16x16x32_bf16(Bt[n][k], At[m][k], acc[ai][bj][m][n], 0, 0, 0); __builtin_amdgcn_s_setprio(0); } while (0)
; #define PG8_WAIT_V(n) asm volatile("s_waitcnt vmcnt(" #n ")" ::: "memory")
; #define PG8_WAIT_L(n) asm volatile("s_waitcnt lgkmcnt(" #n ")" ::: "memory")
; #define PG8_BAR __builtin_amdgcn_s_barrier()
; #define PG8_SCHED __builtin_amdgcn_sched_barrier(0)
; template <class Epi, class Sched, bool APERM = false, bool HALFN = false>
; __device__ __forceinline__ void gemm_phase(LAS unsigned char* lds, const int tid_in, const int K, const Sched& S, const Epi& E) {
;     ...
;             PG8_LDA(At, 1, 1); PG8_STAGE(PG8_SB(1, 0), b3, voffB); PG8_STAGE(PG8_SB(1, 1), b3 + hstep, voffB); PG8_STAGE(PG8_SA(1, 0), a3, voffA);
;             PG8_WAIT_V(8); PG8_WAIT_L(0); PG8_BAR; PG8_MMA(1, 0, At, B0); if constexpr (!HALFN) PG8_MMA(1, 1, At, B1); PG8_BAR; PG8_SCHED;
;         }
;         if (wr == 0) PG8_BAR;
	s_add_i32 s20, s57, s28
	v_lshl_add_u64 v[208:209], v[208:209], 0, s[78:79]
	s_mov_b32 m0, s20
	ds_read_b128 v[160:163], v226 offset:49152
	ds_read_b128 v[164:167], v226 offset:50176
	ds_read_b128 v[168:171], v226 offset:51200
	ds_read_b128 v[172:175], v226 offset:52224
	ds_read_b128 v[176:179], v226 offset:53248
	ds_read_b128 v[180:183], v226 offset:54272
	ds_read_b128 v[184:187], v226 offset:55296
	ds_read_b128 v[204:207], v226 offset:56320
	global_load_lds_dwordx4 v[208:209], off
	s_add_i32 m0, s20, 0x2000
	s_add_u32 s18, s18, 0x20080
	v_lshl_add_u64 v[208:209], v[210:211], 0, s[78:79]
	s_addc_u32 s19, s19, 0
	s_add_i32 s20, s70, s28
	global_load_lds_dwordx4 v[208:209], off
	v_lshl_add_u64 v[208:209], s[18:19], 0, v[200:201]
	s_mov_b32 m0, s20
	s_nop 0
	global_load_lds_dwordx4 v[208:209], off
	v_lshl_add_u64 v[208:209], s[18:19], 0, v[192:193]
	s_add_i32 m0, s20, 0x2000
	s_nop 0
	global_load_lds_dwordx4 v[208:209], off
	v_lshl_add_u64 v[208:209], v[212:213], 0, s[78:79]
	s_mov_b32 m0, s35
	s_nop 0
	global_load_lds_dwordx4 v[208:209], off
	v_lshl_add_u64 v[208:209], v[214:215], 0, s[78:79]
	s_mov_b32 m0, s38
	s_nop 0
	global_load_lds_dwordx4 v[208:209], off
	s_waitcnt vmcnt(8)
	s_waitcnt lgkmcnt(0)
	s_barrier
	s_setprio 1
	v_mfma_f32_16x16x32_bf16 v[60:63], v[112:115], v[160:163], v[60:63]
	v_mfma_f32_16x16x32_bf16 v[56:59], v[120:123], v[160:163], v[56:59]
	v_mfma_f32_16x16x32_bf16 v[44:47], v[112:115], v[168:171], v[44:47]
	v_mfma_f32_16x16x32_bf16 v[40:43], v[120:123], v[168:171], v[40:43]
	v_mfma_f32_16x16x32_bf16 v[28:31], v[112:115], v[176:179], v[28:31]
	v_mfma_f32_16x16x32_bf16 v[24:27], v[120:123], v[176:179], v[24:27]
	v_mfma_f32_16x16x32_bf16 v[12:15], v[112:115], v[184:187], v[12:15]
	v_mfma_f32_16x16x32_bf16 v[8:11], v[120:123], v[184:187], v[8:11]
	v_mfma_f32_16x16x32_bf16 v[60:63], v[116:119], v[164:167], v[60:63]
	v_mfma_f32_16x16x32_bf16 v[56:59], v[128:131], v[164:167], v[56:59]
	v_mfma_f32_16x16x32_bf16 v[44:47], v[116:119], v[172:175], v[44:47]
	v_mfma_f32_16x16x32_bf16 v[40:43], v[128:131], v[172:175], v[40:43]
	v_mfma_f32_16x16x32_bf16 v[28:31], v[116:119], v[180:183], v[28:31]
	v_mfma_f32_16x16x32_bf16 v[24:27], v[128:131], v[180:183], v[24:27]
	v_mfma_f32_16x16x32_bf16 v[12:15], v[116:119], v[204:207], v[12:15]
	v_mfma_f32_16x16x32_bf16 v[8:11], v[128:131], v[204:207], v[8:11]
	v_mfma_f32_16x16x32_bf16 v[52:55], v[136:139], v[160:163], v[52:55]
	v_mfma_f32_16x16x32_bf16 v[48:51], v[144:147], v[160:163], v[48:51]
	v_mfma_f32_16x16x32_bf16 v[36:39], v[136:139], v[168:171], v[36:39]
	v_mfma_f32_16x16x32_bf16 v[32:35], v[144:147], v[168:171], v[32:35]
	v_mfma_f32_16x16x32_bf16 v[20:23], v[136:139], v[176:179], v[20:23]
	v_mfma_f32_16x16x32_bf16 v[16:19], v[144:147], v[176:179], v[16:19]
	v_mfma_f32_16x16x32_bf16 v[4:7], v[136:139], v[184:187], v[4:7]
	v_mfma_f32_16x16x32_bf16 v[0:3], v[144:147], v[184:187], v[0:3]
	v_mfma_f32_16x16x32_bf16 v[52:55], v[140:143], v[164:167], v[52:55]
	v_mfma_f32_16x16x32_bf16 v[48:51], v[156:159], v[164:167], v[48:51]
	v_mfma_f32_16x16x32_bf16 v[36:39], v[140:143], v[172:175], v[36:39]
	v_mfma_f32_16x16x32_bf16 v[32:35], v[156:159], v[172:175], v[32:35]
	v_mfma_f32_16x16x32_bf16 v[20:23], v[140:143], v[180:183], v[20:23]
	v_mfma_f32_16x16x32_bf16 v[16:19], v[156:159], v[180:183], v[16:19]
	v_mfma_f32_16x16x32_bf16 v[4:7], v[140:143], v[204:207], v[4:7]
	v_mfma_f32_16x16x32_bf16 v[0:3], v[156:159], v[204:207], v[0:3]
	s_setprio 0
	s_barrier
	s_add_i32 s53, s53, 2
	s_add_u32 s45, s45, 0x100
	s_addc_u32 s52, s52, 0
	s_add_u32 s16, s16, 0x100
	s_addc_u32 s17, s17, 0
	s_cmp_gt_u32 s53, 5
	s_cbranch_scc0 .LBB0_806
	s_and_b64 vcc, exec, s[8:9]
	s_cbranch_vccz .LBB0_809
	s_barrier

; #define PG8_STAGE(bufoff, gbase, voff) do { _Pragma("unroll") for (int _i = 0; _i < 2; ++_i) \
;         __builtin_amdgcn_global_load_lds((const unsigned*)((const char*)(gbase) + (voff)[_i]), (LAS unsigned*)(lds + (bufoff) + ldsw + _i * 8192), 16, 0, 0); } while (0)
; #define PG8_LDA(dst, b, h) do { _Pragma("unroll") for (int m = 0; m < 4; ++m) _Pragma("unroll") for (int k = 0; k < 2; ++k) dst[m][k] = *(const LAS bf16x8*)(lds + PG8_SA(b, h) + aoff + m * 2048 + k * 1024); } while (0)
; #define PG8_LDB(dst, b, h) do { _Pragma("unroll") for (int n = 0; n < 2; ++n) _Pragma("unroll") for (int k = 0; k < 2; ++k) dst[n][k] = *(const LAS bf16x8*)(lds + PG8_SB(b, h) + boff + n * 2048 + k * 1024); } while (0)
; #define PG8_MMA(ai, bj, At, Bt) do { __builtin_amdgcn_s_setprio(1); _Pragma("unroll") for (int m = 0; m < 4; ++m) _Pragma("unroll") for (int n = 0; n < 2; ++n) _Pragma("unroll") for (int k = 0; k < 2; ++k) \
;         acc[ai][bj][m][n] = __builtin_amdgcn_mfma_f32_16x16x32_bf16(Bt[n][k], At[m][k], acc[ai][bj][m][n], 0, 0, 0); __builtin_amdgcn_s_setprio(0); } while (0)
; #define PG8_WAIT_V(n) asm volatile("s_waitcnt vmcnt(" #n ")" ::: "memory")
; #define PG8_WAIT_L(n) asm volatile("s_waitcnt lgkmcnt(" #n ")" ::: "memory")
; #define PG8_BAR __builtin_amdgcn_s_barrier()
; template <class Epi, class Sched, bool APERM = false, bool HALFN = false>
; __device__ __forceinline__ void gemm_phase(LAS unsigned char* lds, const int tid_in, const int K, const Sched& S, const Epi& E) {
;     ...
;             const bool last = (t == nt - 2);
;             const char* a1 = cA + (size_t)(t + 1) * kstep;
;             const char* a2 = last ? nA : cA + (size_t)(t + 2) * kstep; const char* b2 = last ? nB : cB + (size_t)(t + 2) * kstep;
;             const char* a3 = a2 + kstep; const char* b3 = b2 + kstep;
;             PG8_LDB(B0, 0, 0); PG8_LDB(B1, 0, 1); PG8_SCHED; PG8_LDA(At, 0, 0); PG8_STAGE(PG8_SA(1, 1), a1 + hstepA, voffA);
;             PG8_WAIT_V(8); PG8_WAIT_L(0); PG8_BAR; PG8_MMA(0, 0, At, B0); if constexpr (!HALFN) PG8_MMA(0, 1, At, B1); PG8_BAR; PG8_SCHED;
;             PG8_LDA(At, 0, 1); PG8_STAGE(PG8_SB(0, 0), b2, voffB); PG8_STAGE(PG8_SB(0, 1), b2 + hstep, voffB); PG8_STAGE(PG8_SA(0, 0), a2, voffA);
;             PG8_WAIT_V(8); PG8_WAIT_L(0); PG8_BAR; PG8_MMA(1, 0, At, B0); if constexpr (!HALFN) PG8_MMA(1, 1, At, B1); PG8_BAR; PG8_SCHED;
.LBB0_902:
	s_add_u32 s4, s0, 0x100
	s_addc_u32 s5, s1, 0
	s_add_i32 s14, 0, 0x10000
	s_cmp_eq_u32 s13, 28
	s_cselect_b32 s9, s23, s5
	s_cselect_b32 s8, s22, s4
	v_add_u32_e32 v52, s14, v202
	s_cselect_b32 s7, s25, s12
	s_cselect_b32 s6, s24, s11
	s_add_i32 s15, 0, 0x14000
	ds_read_b128 v[62:65], v52
	ds_read_b128 v[128:131], v52 offset:1024
	ds_read_b128 v[132:135], v52 offset:2048
	ds_read_b128 v[136:139], v52 offset:3072
	v_add_u32_e32 v52, s15, v202
	ds_read_b128 v[140:143], v52
	ds_read_b128 v[152:155], v52 offset:1024
	ds_read_b128 v[156:159], v52 offset:2048
	ds_read_b128 v[160:163], v52 offset:3072
	v_lshl_add_u64 v[52:53], s[0:1], 0, v[214:215]
	s_add_i32 m0, s57, 0xc000
	ds_read_b128 v[164:167], v243
	ds_read_b128 v[168:171], v243 offset:1024
	ds_read_b128 v[172:175], v243 offset:2048
	ds_read_b128 v[176:179], v243 offset:3072
	ds_read_b128 v[180:183], v243 offset:4096
	ds_read_b128 v[184:187], v243 offset:5120
	ds_read_b128 v[188:191], v243 offset:6144
	ds_read_b128 v[192:195], v243 offset:7168
	global_load_lds_dwordx4 v[52:53], off
	v_lshl_add_u64 v[52:53], s[0:1], 0, v[212:213]
	s_add_i32 m0, s57, 0xe000
	s_nop 0
	global_load_lds_dwordx4 v[52:53], off
	s_waitcnt vmcnt(8)
	s_waitcnt lgkmcnt(0)
	s_barrier
	s_setprio 1
	v_mfma_f32_16x16x32_bf16 v[148:151], v[62:65], v[164:167], v[148:151]
	v_mfma_f32_16x16x32_bf16 v[58:61], v[132:135], v[164:167], v[58:61]
	v_mfma_f32_16x16x32_bf16 v[124:127], v[62:65], v[172:175], v[124:127]
	v_mfma_f32_16x16x32_bf16 v[36:39], v[132:135], v[172:175], v[36:39]
	v_mfma_f32_16x16x32_bf16 v[116:119], v[62:65], v[180:183], v[116:119]
	v_mfma_f32_16x16x32_bf16 v[28:31], v[132:135], v[180:183], v[28:31]
	v_mfma_f32_16x16x32_bf16 v[108:111], v[62:65], v[188:191], v[108:111]
	v_mfma_f32_16x16x32_bf16 v[20:23], v[132:135], v[188:191], v[20:23]
	v_mfma_f32_16x16x32_bf16 v[148:151], v[128:131], v[168:171], v[148:151]
	v_mfma_f32_16x16x32_bf16 v[58:61], v[136:139], v[168:171], v[58:61]
	v_mfma_f32_16x16x32_bf16 v[124:127], v[128:131], v[176:179], v[124:127]
	v_mfma_f32_16x16x32_bf16 v[36:39], v[136:139], v[176:179], v[36:39]
	v_mfma_f32_16x16x32_bf16 v[116:119], v[128:131], v[184:187], v[116:119]
	v_mfma_f32_16x16x32_bf16 v[28:31], v[136:139], v[184:187], v[28:31]
	v_mfma_f32_16x16x32_bf16 v[108:111], v[128:131], v[192:195], v[108:111]
	v_mfma_f32_16x16x32_bf16 v[20:23], v[136:139], v[192:195], v[20:23]
	v_mfma_f32_16x16x32_bf16 v[144:147], v[140:143], v[164:167], v[144:147]
	v_mfma_f32_16x16x32_bf16 v[40:43], v[156:159], v[164:167], v[40:43]
	v_mfma_f32_16x16x32_bf16 v[120:123], v[140:143], v[172:175], v[120:123]
	v_mfma_f32_16x16x32_bf16 v[32:35], v[156:159], v[172:175], v[32:35]
	v_mfma_f32_16x16x32_bf16 v[112:115], v[140:143], v[180:183], v[112:115]
	v_mfma_f32_16x16x32_bf16 v[24:27], v[156:159], v[180:183], v[24:27]
	v_mfma_f32_16x16x32_bf16 v[104:107], v[140:143], v[188:191], v[104:107]
	v_mfma_f32_16x16x32_bf16 v[16:19], v[156:159], v[188:191], v[16:19]
	v_mfma_f32_16x16x32_bf16 v[144:147], v[152:155], v[168:171], v[144:147]
	v_mfma_f32_16x16x32_bf16 v[40:43], v[160:163], v[168:171], v[40:43]
	v_mfma_f32_16x16x32_bf16 v[120:123], v[152:155], v[176:179], v[120:123]
	v_mfma_f32_16x16x32_bf16 v[32:35], v[160:163], v[176:179], v[32:35]
	v_mfma_f32_16x16x32_bf16 v[112:115], v[152:155], v[184:187], v[112:115]
	v_mfma_f32_16x16x32_bf16 v[24:27], v[160:163], v[184:187], v[24:27]
	v_mfma_f32_16x16x32_bf16 v[104:107], v[152:155], v[192:195], v[104:107]
	v_mfma_f32_16x16x32_bf16 v[16:19], v[160:163], v[192:195], v[16:19]
	s_setprio 0
	s_barrier
	s_add_i32 s0, s14, s39
	v_lshl_add_u64 v[196:197], s[6:7], 0, v[206:207]
	s_mov_b32 m0, s0
	ds_read_b128 v[164:167], v243 offset:16384
	ds_read_b128 v[168:171], v243 offset:17408
	ds_read_b128 v[172:175], v243 offset:18432
	ds_read_b128 v[176:179], v243 offset:19456
	ds_read_b128 v[180:183], v243 offset:20480
	ds_read_b128 v[184:187], v243 offset:21504
	ds_read_b128 v[188:191], v243 offset:22528
	ds_read_b128 v[192:195], v243 offset:23552
	global_load_lds_dwordx4 v[196:197], off
	s_add_i32 m0, s0, 0x2000
	s_add_u32 s0, s6, 0x80000
	v_lshl_add_u64 v[198:199], s[6:7], 0, v[210:211]
	s_addc_u32 s1, s7, 0
	s_add_i32 s14, s15, s39
	global_load_lds_dwordx4 v[198:199], off
	v_lshl_add_u64 v[52:53], s[0:1], 0, v[206:207]
	s_mov_b32 m0, s14
	v_lshl_add_u64 v[216:217], s[8:9], 0, v[204:205]
	global_load_lds_dwordx4 v[52:53], off
	v_lshl_add_u64 v[52:53], s[0:1], 0, v[210:211]
	s_add_i32 m0, s14, 0x2000
	v_lshl_add_u64 v[218:219], s[8:9], 0, v[208:209]
	global_load_lds_dwordx4 v[52:53], off
	s_mov_b32 m0, s57
	s_nop 0
	global_load_lds_dwordx4 v[216:217], off
	s_mov_b32 m0, s70
	s_nop 0
	global_load_lds_dwordx4 v[218:219], off
	s_waitcnt vmcnt(8)
	s_waitcnt lgkmcnt(0)
	s_barrier
; #define PG8_STAGE(bufoff, gbase, voff) do { _Pragma("unroll") for (int _i = 0; _i < 2; ++_i) \
;         __builtin_amdgcn_global_load_lds((const unsigned*)((const char*)(gbase) + (voff)[_i]), (LAS unsigned*)(lds + (bufoff) + ldsw + _i * 8192), 16, 0, 0); } while (0)
; #define PG8_LDA(dst, b, h) do { _Pragma("unroll") for (int m = 0; m < 4; ++m) _Pragma("unroll") for (int k = 0; k < 2; ++k) dst[m][k] = *(const LAS bf16x8*)(lds + PG8_SA(b, h) + aoff + m * 2048 + k * 1024); } while (0)
; #define PG8_LDB(dst, b, h) do { _Pragma("unroll") for (int n = 0; n < 2; ++n) _Pragma("unroll") for (int k = 0; k < 2; ++k) dst[n][k] = *(const LAS bf16x8*)(lds + PG8_SB(b, h) + boff + n * 2048 + k * 1024); } while (0)
; #define PG8_MMA(ai, bj, At, Bt) do { __builtin_amdgcn_s_setprio(1); _Pragma("unroll") for (int m = 0; m < 4; ++m) _Pragma("unroll") for (int n = 0; n < 2; ++n) _Pragma("unroll") for (int k = 0; k < 2; ++k) \
;         acc[ai][bj][m][n] = __builtin_amdgcn_mfma_f32_16x16x32_bf16(Bt[n][k], At[m][k], acc[ai][bj][m][n], 0, 0, 0); __builtin_amdgcn_s_setprio(0); } while (0)
; #define PG8_WAIT_V(n) asm volatile("s_waitcnt vmcnt(" #n ")" ::: "memory")
; #define PG8_WAIT_L(n) asm volatile("s_waitcnt lgkmcnt(" #n ")" ::: "memory")
; #define PG8_BAR __builtin_amdgcn_s_barrier()
; #define PG8_SCHED __builtin_amdgcn_sched_barrier(0)
; template <class Epi, class Sched, bool APERM = false, bool HALFN = false>
; __device__ __forceinline__ void gemm_phase(LAS unsigned char* lds, const int tid_in, const int K, const Sched& S, const Epi& E) {
;     ...
;             PG8_WAIT_V(8); PG8_WAIT_L(0); PG8_BAR; PG8_MMA(1, 0, At, B0); if constexpr (!HALFN) PG8_MMA(1, 1, At, B1); PG8_BAR; PG8_SCHED;
;             PG8_LDB(B0, 1, 0); PG8_LDB(B1, 1, 1); PG8_SCHED; PG8_LDA(At, 1, 0); PG8_STAGE(PG8_SA(0, 1), a2 + hstepA, voffA);
;             PG8_WAIT_V(8); PG8_WAIT_L(0); PG8_BAR; PG8_MMA(0, 0, At, B0); if constexpr (!HALFN) PG8_MMA(0, 1, At, B1); PG8_BAR; PG8_SCHED;
	s_setprio 1
	v_mfma_f32_16x16x32_bf16 v[100:103], v[62:65], v[164:167], v[100:103]
	v_mfma_f32_16x16x32_bf16 v[12:15], v[132:135], v[164:167], v[12:15]
	v_mfma_f32_16x16x32_bf16 v[92:95], v[62:65], v[172:175], v[92:95]
	v_mfma_f32_16x16x32_bf16 v[4:7], v[132:135], v[172:175], v[4:7]
	v_mfma_f32_16x16x32_bf16 v[48:51], v[62:65], v[180:183], v[48:51]
	v_mfma_f32_16x16x32_bf16 v[72:75], v[132:135], v[180:183], v[72:75]
	v_mfma_f32_16x16x32_bf16 v[66:69], v[132:135], v[188:191], v[68:71]
	v_mfma_f32_16x16x32_bf16 v[100:103], v[128:131], v[168:171], v[100:103]
	v_mfma_f32_16x16x32_bf16 v[12:15], v[136:139], v[168:171], v[12:15]
	v_mfma_f32_16x16x32_bf16 v[92:95], v[128:131], v[176:179], v[92:95]
	v_mfma_f32_16x16x32_bf16 v[4:7], v[136:139], v[176:179], v[4:7]
	v_mfma_f32_16x16x32_bf16 v[48:51], v[128:131], v[184:187], v[48:51]
	v_mfma_f32_16x16x32_bf16 v[72:75], v[136:139], v[184:187], v[72:75]
	v_mfma_f32_16x16x32_bf16 v[62:65], v[62:65], v[188:191], v[80:83]
	v_mfma_f32_16x16x32_bf16 v[66:69], v[136:139], v[192:195], v[66:69]
	v_mfma_f32_16x16x32_bf16 v[62:65], v[128:131], v[192:195], v[62:65]
	v_mfma_f32_16x16x32_bf16 v[80:83], v[140:143], v[164:167], v[96:99]
	v_mfma_f32_16x16x32_bf16 v[96:99], v[152:155], v[168:171], v[80:83]
	v_mfma_f32_16x16x32_bf16 v[80:83], v[140:143], v[172:175], v[88:91]
	v_mfma_f32_16x16x32_bf16 v[8:11], v[156:159], v[164:167], v[8:11]
	v_mfma_f32_16x16x32_bf16 v[88:91], v[152:155], v[176:179], v[80:83]
	v_mfma_f32_16x16x32_bf16 v[0:3], v[156:159], v[172:175], v[0:3]
	v_mfma_f32_16x16x32_bf16 v[80:83], v[140:143], v[180:183], v[84:87]
	v_mfma_f32_16x16x32_bf16 v[52:55], v[156:159], v[180:183], v[54:57]
	v_mfma_f32_16x16x32_bf16 v[76:79], v[140:143], v[188:191], v[76:79]
	v_mfma_f32_16x16x32_bf16 v[44:47], v[156:159], v[188:191], v[44:47]
	v_mfma_f32_16x16x32_bf16 v[8:11], v[160:163], v[168:171], v[8:11]
	v_mfma_f32_16x16x32_bf16 v[0:3], v[160:163], v[176:179], v[0:3]
	v_mfma_f32_16x16x32_bf16 v[84:87], v[152:155], v[184:187], v[80:83]
	v_mfma_f32_16x16x32_bf16 v[52:55], v[160:163], v[184:187], v[52:55]
	v_mfma_f32_16x16x32_bf16 v[76:79], v[152:155], v[192:195], v[76:79]
	v_mfma_f32_16x16x32_bf16 v[44:47], v[160:163], v[192:195], v[44:47]
	s_setprio 0
	s_barrier
	s_add_i32 s14, 0, 0x18000
	v_add_u32_e32 v56, s14, v202
	s_add_i32 s15, 0, 0x1c000
	ds_read_b128 v[80:83], v56
	ds_read_b128 v[128:131], v56 offset:1024
	ds_read_b128 v[132:135], v56 offset:2048
	ds_read_b128 v[136:139], v56 offset:3072
	v_add_u32_e32 v56, s15, v202
	ds_read_b128 v[140:143], v56
	ds_read_b128 v[152:155], v56 offset:1024
	ds_read_b128 v[156:159], v56 offset:2048
	ds_read_b128 v[160:163], v56 offset:3072
	s_add_u32 s0, s8, 0x4000
	s_addc_u32 s1, s9, 0
	s_mov_b32 m0, s71
	v_lshl_add_u64 v[56:57], s[0:1], 0, v[204:205]
	ds_read_b128 v[164:167], v243 offset:32768
	ds_read_b128 v[168:171], v243 offset:33792
	ds_read_b128 v[172:175], v243 offset:34816
	ds_read_b128 v[176:179], v243 offset:35840
	ds_read_b128 v[180:183], v243 offset:36864
	ds_read_b128 v[184:187], v243 offset:37888
	ds_read_b128 v[188:191], v243 offset:38912
	ds_read_b128 v[192:195], v243 offset:39936
	global_load_lds_dwordx4 v[56:57], off
	v_lshl_add_u64 v[56:57], s[0:1], 0, v[208:209]
	s_mov_b32 m0, s72
	s_nop 0
	global_load_lds_dwordx4 v[56:57], off
	s_waitcnt vmcnt(8)
	s_waitcnt lgkmcnt(0)
	s_barrier
	s_setprio 1
	v_mfma_f32_16x16x32_bf16 v[148:151], v[80:83], v[164:167], v[148:151]
	v_mfma_f32_16x16x32_bf16 v[56:59], v[132:135], v[164:167], v[58:61]
	v_mfma_f32_16x16x32_bf16 v[124:127], v[80:83], v[172:175], v[124:127]
	v_mfma_f32_16x16x32_bf16 v[36:39], v[132:135], v[172:175], v[36:39]
	v_mfma_f32_16x16x32_bf16 v[116:119], v[80:83], v[180:183], v[116:119]
	v_mfma_f32_16x16x32_bf16 v[28:31], v[132:135], v[180:183], v[28:31]
	v_mfma_f32_16x16x32_bf16 v[108:111], v[80:83], v[188:191], v[108:111]
	v_mfma_f32_16x16x32_bf16 v[20:23], v[132:135], v[188:191], v[20:23]
	v_mfma_f32_16x16x32_bf16 v[148:151], v[128:131], v[168:171], v[148:151]
	v_mfma_f32_16x16x32_bf16 v[58:61], v[136:139], v[168:171], v[56:59]
	v_mfma_f32_16x16x32_bf16 v[124:127], v[128:131], v[176:179], v[124:127]
	v_mfma_f32_16x16x32_bf16 v[36:39], v[136:139], v[176:179], v[36:39]
	v_mfma_f32_16x16x32_bf16 v[116:119], v[128:131], v[184:187], v[116:119]
	v_mfma_f32_16x16x32_bf16 v[28:31], v[136:139], v[184:187], v[28:31]
	v_mfma_f32_16x16x32_bf16 v[108:111], v[128:131], v[192:195], v[108:111]
	v_mfma_f32_16x16x32_bf16 v[20:23], v[136:139], v[192:195], v[20:23]
	v_mfma_f32_16x16x32_bf16 v[144:147], v[140:143], v[164:167], v[144:147]
	v_mfma_f32_16x16x32_bf16 v[40:43], v[156:159], v[164:167], v[40:43]
	v_mfma_f32_16x16x32_bf16 v[120:123], v[140:143], v[172:175], v[120:123]
	v_mfma_f32_16x16x32_bf16 v[32:35], v[156:159], v[172:175], v[32:35]
	v_mfma_f32_16x16x32_bf16 v[112:115], v[140:143], v[180:183], v[112:115]
	v_mfma_f32_16x16x32_bf16 v[24:27], v[156:159], v[180:183], v[24:27]
	v_mfma_f32_16x16x32_bf16 v[104:107], v[140:143], v[188:191], v[104:107]
	v_mfma_f32_16x16x32_bf16 v[16:19], v[156:159], v[188:191], v[16:19]
	v_mfma_f32_16x16x32_bf16 v[144:147], v[152:155], v[168:171], v[144:147]
	v_mfma_f32_16x16x32_bf16 v[40:43], v[160:163], v[168:171], v[40:43]
	v_mfma_f32_16x16x32_bf16 v[120:123], v[152:155], v[176:179], v[120:123]
	v_mfma_f32_16x16x32_bf16 v[32:35], v[160:163], v[176:179], v[32:35]
	v_mfma_f32_16x16x32_bf16 v[112:115], v[152:155], v[184:187], v[112:115]
	v_mfma_f32_16x16x32_bf16 v[24:27], v[160:163], v[184:187], v[24:27]
	v_mfma_f32_16x16x32_bf16 v[104:107], v[152:155], v[192:195], v[104:107]
	v_mfma_f32_16x16x32_bf16 v[16:19], v[160:163], v[192:195], v[16:19]
	s_setprio 0
	s_barrier
; #define PG8_STAGE(bufoff, gbase, voff) do { _Pragma("unroll") for (int _i = 0; _i < 2; ++_i) \
;         __builtin_amdgcn_global_load_lds((const unsigned*)((const char*)(gbase) + (voff)[_i]), (LAS unsigned*)(lds + (bufoff) + ldsw + _i * 8192), 16, 0, 0); } while (0)
; #define PG8_LDA(dst, b, h) do { _Pragma("unroll") for (int m = 0; m < 4; ++m) _Pragma("unroll") for (int k = 0; k < 2; ++k) dst[m][k] = *(const LAS bf16x8*)(lds + PG8_SA(b, h) + aoff + m * 2048 + k * 1024); } while (0)
; #define PG8_MMA(ai, bj, At, Bt) do { __builtin_amdgcn_s_setprio(1); _Pragma("unroll") for (int m = 0; m < 4; ++m) _Pragma("unroll") for (int n = 0; n < 2; ++n) _Pragma("unroll") for (int k = 0; k < 2; ++k) \
;         acc[ai][bj][m][n] = __builtin_amdgcn_mfma_f32_16x16x32_bf16(Bt[n][k], At[m][k], acc[ai][bj][m][n], 0, 0, 0); __builtin_amdgcn_s_setprio(0); } while (0)
; #define PG8_WAIT_V(n) asm volatile("s_waitcnt vmcnt(" #n ")" ::: "memory")
; #define PG8_WAIT_L(n) asm volatile("s_waitcnt lgkmcnt(" #n ")" ::: "memory")
; #define PG8_BAR __builtin_amdgcn_s_barrier()
; #define PG8_SCHED __builtin_amdgcn_sched_barrier(0)
; template <class Epi, class Sched, bool APERM = false, bool HALFN = false>
; __device__ __forceinline__ void gemm_phase(LAS unsigned char* lds, const int tid_in, const int K, const Sched& S, const Epi& E) {
;     ...
;             PG8_LDA(At, 1, 1); PG8_STAGE(PG8_SB(1, 0), b3, voffB); PG8_STAGE(PG8_SB(1, 1), b3 + hstep, voffB); PG8_STAGE(PG8_SA(1, 0), a3, voffA);
;             PG8_WAIT_V(8); PG8_WAIT_L(0); PG8_BAR; PG8_MMA(1, 0, At, B0); if constexpr (!HALFN) PG8_MMA(1, 1, At, B1); PG8_BAR; PG8_SCHED;
;         }
;         if (wr == 0) PG8_BAR;
	s_add_i32 s0, s14, s39
	v_lshl_add_u64 v[56:57], v[196:197], 0, s[78:79]
	s_mov_b32 m0, s0
	ds_read_b128 v[164:167], v243 offset:49152
	ds_read_b128 v[168:171], v243 offset:50176
	ds_read_b128 v[172:175], v243 offset:51200
	ds_read_b128 v[176:179], v243 offset:52224
	ds_read_b128 v[180:183], v243 offset:53248
	ds_read_b128 v[184:187], v243 offset:54272
	ds_read_b128 v[188:191], v243 offset:55296
	ds_read_b128 v[192:195], v243 offset:56320
	global_load_lds_dwordx4 v[56:57], off
	s_add_i32 m0, s0, 0x2000
	s_add_u32 s0, s6, 0x80080
	v_lshl_add_u64 v[56:57], v[198:199], 0, s[78:79]
	s_addc_u32 s1, s7, 0
	s_add_i32 s6, s15, s39
	global_load_lds_dwordx4 v[56:57], off
	v_lshl_add_u64 v[56:57], s[0:1], 0, v[206:207]
	s_mov_b32 m0, s6
	s_nop 0
	global_load_lds_dwordx4 v[56:57], off
	v_lshl_add_u64 v[56:57], s[0:1], 0, v[210:211]
	s_add_i32 m0, s6, 0x2000
	s_nop 0
	global_load_lds_dwordx4 v[56:57], off
	v_lshl_add_u64 v[56:57], v[216:217], 0, s[78:79]
	s_mov_b32 m0, s81
	s_nop 0
	global_load_lds_dwordx4 v[56:57], off
	v_lshl_add_u64 v[56:57], v[218:219], 0, s[78:79]
	s_mov_b32 m0, s86
	s_nop 0
	global_load_lds_dwordx4 v[56:57], off
	s_waitcnt vmcnt(8)
	s_waitcnt lgkmcnt(0)
	s_barrier
	s_setprio 1
	v_mfma_f32_16x16x32_bf16 v[62:65], v[80:83], v[188:191], v[62:65]
	v_mfma_f32_16x16x32_bf16 v[100:103], v[80:83], v[164:167], v[100:103]
	v_mfma_f32_16x16x32_bf16 v[12:15], v[132:135], v[164:167], v[12:15]
	v_mfma_f32_16x16x32_bf16 v[92:95], v[80:83], v[172:175], v[92:95]
	v_mfma_f32_16x16x32_bf16 v[4:7], v[132:135], v[172:175], v[4:7]
	v_mfma_f32_16x16x32_bf16 v[48:51], v[80:83], v[180:183], v[48:51]
	v_mfma_f32_16x16x32_bf16 v[70:73], v[132:135], v[180:183], v[72:75]
	v_mfma_f32_16x16x32_bf16 v[80:83], v[128:131], v[192:195], v[62:65]
	v_mfma_f32_16x16x32_bf16 v[62:65], v[132:135], v[188:191], v[66:69]
	v_mfma_f32_16x16x32_bf16 v[100:103], v[128:131], v[168:171], v[100:103]
	v_mfma_f32_16x16x32_bf16 v[12:15], v[136:139], v[168:171], v[12:15]
	v_mfma_f32_16x16x32_bf16 v[92:95], v[128:131], v[176:179], v[92:95]
	v_mfma_f32_16x16x32_bf16 v[4:7], v[136:139], v[176:179], v[4:7]
	v_mfma_f32_16x16x32_bf16 v[48:51], v[128:131], v[184:187], v[48:51]
	v_mfma_f32_16x16x32_bf16 v[72:75], v[136:139], v[184:187], v[70:73]
	v_mfma_f32_16x16x32_bf16 v[68:71], v[136:139], v[192:195], v[62:65]
	v_mfma_f32_16x16x32_bf16 v[62:65], v[140:143], v[164:167], v[96:99]
	v_mfma_f32_16x16x32_bf16 v[96:99], v[152:155], v[168:171], v[62:65]
	v_mfma_f32_16x16x32_bf16 v[62:65], v[140:143], v[172:175], v[88:91]
	v_mfma_f32_16x16x32_bf16 v[88:91], v[152:155], v[176:179], v[62:65]
	v_mfma_f32_16x16x32_bf16 v[62:65], v[140:143], v[180:183], v[84:87]
	v_mfma_f32_16x16x32_bf16 v[8:11], v[156:159], v[164:167], v[8:11]
	v_mfma_f32_16x16x32_bf16 v[0:3], v[156:159], v[172:175], v[0:3]
	v_mfma_f32_16x16x32_bf16 v[84:87], v[152:155], v[184:187], v[62:65]
	v_mfma_f32_16x16x32_bf16 v[52:55], v[156:159], v[180:183], v[52:55]
	v_mfma_f32_16x16x32_bf16 v[62:65], v[140:143], v[188:191], v[76:79]
	v_mfma_f32_16x16x32_bf16 v[44:47], v[156:159], v[188:191], v[44:47]
	v_mfma_f32_16x16x32_bf16 v[8:11], v[160:163], v[168:171], v[8:11]
	v_mfma_f32_16x16x32_bf16 v[0:3], v[160:163], v[176:179], v[0:3]
	v_mfma_f32_16x16x32_bf16 v[54:57], v[160:163], v[184:187], v[52:55]
	v_mfma_f32_16x16x32_bf16 v[76:79], v[152:155], v[192:195], v[62:65]
	v_mfma_f32_16x16x32_bf16 v[44:47], v[160:163], v[192:195], v[44:47]
	s_setprio 0
	s_barrier
	s_add_i32 s13, s13, 2
	s_add_u32 s11, s11, 0x100
	s_addc_u32 s12, s12, 0
	s_cmp_gt_u32 s13, 29
	s_mov_b64 s[0:1], s[4:5]
	s_cbranch_scc0 .LBB0_902
	s_and_b64 vcc, exec, s[16:17]
	s_cbranch_vccz .LBB0_905
	s_barrier

; #define PG8_STAGE(bufoff, gbase, voff) do { _Pragma("unroll") for (int _i = 0; _i < 2; ++_i) \
;         __builtin_amdgcn_global_load_lds((const unsigned*)((const char*)(gbase) + (voff)[_i]), (LAS unsigned*)(lds + (bufoff) + ldsw + _i * 8192), 16, 0, 0); } while (0)
; #define PG8_LDA(dst, b, h) do { _Pragma("unroll") for (int m = 0; m < 4; ++m) _Pragma("unroll") for (int k = 0; k < 2; ++k) dst[m][k] = *(const LAS bf16x8*)(lds + PG8_SA(b, h) + aoff + m * 2048 + k * 1024); } while (0)
; #define PG8_LDB(dst, b, h) do { _Pragma("unroll") for (int n = 0; n < 2; ++n) _Pragma("unroll") for (int k = 0; k < 2; ++k) dst[n][k] = *(const LAS bf16x8*)(lds + PG8_SB(b, h) + boff + n * 2048 + k * 1024); } while (0)
; #define PG8_MMA(ai, bj, At, Bt) do { __builtin_amdgcn_s_setprio(1); _Pragma("unroll") for (int m = 0; m < 4; ++m) _Pragma("unroll") for (int n = 0; n < 2; ++n) _Pragma("unroll") for (int k = 0; k < 2; ++k) \
;         acc[ai][bj][m][n] = __builtin_amdgcn_mfma_f32_16x16x32_bf16(Bt[n][k], At[m][k], acc[ai][bj][m][n], 0, 0, 0); __builtin_amdgcn_s_setprio(0); } while (0)
; #define PG8_WAIT_V(n) asm volatile("s_waitcnt vmcnt(" #n ")" ::: "memory")
; #define PG8_WAIT_L(n) asm volatile("s_waitcnt lgkmcnt(" #n ")" ::: "memory")
; #define PG8_BAR __builtin_amdgcn_s_barrier()
; template <class Epi, class Sched, bool APERM = false, bool HALFN = false>
; __device__ __forceinline__ void gemm_phase(LAS unsigned char* lds, const int tid_in, const int K, const Sched& S, const Epi& E) {
;     ...
;             const bool last = (t == nt - 2);
;             const char* a1 = cA + (size_t)(t + 1) * kstep;
;             const char* a2 = last ? nA : cA + (size_t)(t + 2) * kstep; const char* b2 = last ? nB : cB + (size_t)(t + 2) * kstep;
;             const char* a3 = a2 + kstep; const char* b3 = b2 + kstep;
;             PG8_LDB(B0, 0, 0); PG8_LDB(B1, 0, 1); PG8_SCHED; PG8_LDA(At, 0, 0); PG8_STAGE(PG8_SA(1, 1), a1 + hstepA, voffA);
;             PG8_WAIT_V(8); PG8_WAIT_L(0); PG8_BAR; PG8_MMA(0, 0, At, B0); if constexpr (!HALFN) PG8_MMA(0, 1, At, B1); PG8_BAR; PG8_SCHED;
;             PG8_LDA(At, 0, 1); PG8_STAGE(PG8_SB(0, 0), b2, voffB); PG8_STAGE(PG8_SB(0, 1), b2 + hstep, voffB); PG8_STAGE(PG8_SA(0, 0), a2, voffA);
;             PG8_WAIT_V(8); PG8_WAIT_L(0); PG8_BAR; PG8_MMA(1, 0, At, B0); if constexpr (!HALFN) PG8_MMA(1, 1, At, B1); PG8_BAR; PG8_SCHED;
.LBB0_1033:
	s_add_u32 s18, s16, 0x100
	s_addc_u32 s19, s17, 0
	s_add_i32 s71, 0, 0x10000
	s_cmpk_eq_i32 s70, 0x54
	s_cselect_b32 s23, s11, s19
	s_cselect_b32 s22, s10, s18
	s_cselect_b32 s21, s13, s57
	s_cselect_b32 s20, s12, s53
	s_add_i32 s72, 0, 0x14000
	v_add_u32_e32 v128, s71, v220
	v_add_u32_e32 v156, s72, v220
	ds_read_b128 v[112:115], v128
	ds_read_b128 v[116:119], v128 offset:1024
	ds_read_b128 v[120:123], v128 offset:2048
	ds_read_b128 v[128:131], v128 offset:3072
	ds_read_b128 v[136:139], v156
	ds_read_b128 v[140:143], v156 offset:1024
	ds_read_b128 v[144:147], v156 offset:2048
	ds_read_b128 v[156:159], v156 offset:3072
	v_lshl_add_u64 v[208:209], s[16:17], 0, v[198:199]
	s_add_i32 m0, s31, 0xc000
	ds_read_b128 v[160:163], v226
	ds_read_b128 v[164:167], v226 offset:1024
	ds_read_b128 v[168:171], v226 offset:2048
	ds_read_b128 v[172:175], v226 offset:3072
	ds_read_b128 v[176:179], v226 offset:4096
	ds_read_b128 v[180:183], v226 offset:5120
	ds_read_b128 v[184:187], v226 offset:6144
	ds_read_b128 v[204:207], v226 offset:7168
	global_load_lds_dwordx4 v[208:209], off
	v_lshl_add_u64 v[208:209], s[16:17], 0, v[196:197]
	s_add_i32 m0, s31, 0xe000
	s_nop 0
	global_load_lds_dwordx4 v[208:209], off
	s_waitcnt vmcnt(8)
	s_waitcnt lgkmcnt(0)
	s_barrier
	s_setprio 1
	v_mfma_f32_16x16x32_bf16 v[152:155], v[112:115], v[160:163], v[152:155]
	v_mfma_f32_16x16x32_bf16 v[148:151], v[120:123], v[160:163], v[148:151]
	v_mfma_f32_16x16x32_bf16 v[108:111], v[112:115], v[168:171], v[108:111]
	v_mfma_f32_16x16x32_bf16 v[104:107], v[120:123], v[168:171], v[104:107]
	v_mfma_f32_16x16x32_bf16 v[92:95], v[112:115], v[176:179], v[92:95]
	v_mfma_f32_16x16x32_bf16 v[88:91], v[120:123], v[176:179], v[88:91]
	v_mfma_f32_16x16x32_bf16 v[76:79], v[112:115], v[184:187], v[76:79]
	v_mfma_f32_16x16x32_bf16 v[72:75], v[120:123], v[184:187], v[72:75]
	v_mfma_f32_16x16x32_bf16 v[152:155], v[116:119], v[164:167], v[152:155]
	v_mfma_f32_16x16x32_bf16 v[148:151], v[128:131], v[164:167], v[148:151]
	v_mfma_f32_16x16x32_bf16 v[108:111], v[116:119], v[172:175], v[108:111]
	v_mfma_f32_16x16x32_bf16 v[104:107], v[128:131], v[172:175], v[104:107]
	v_mfma_f32_16x16x32_bf16 v[92:95], v[116:119], v[180:183], v[92:95]
	v_mfma_f32_16x16x32_bf16 v[88:91], v[128:131], v[180:183], v[88:91]
	v_mfma_f32_16x16x32_bf16 v[76:79], v[116:119], v[204:207], v[76:79]
	v_mfma_f32_16x16x32_bf16 v[72:75], v[128:131], v[204:207], v[72:75]
	v_mfma_f32_16x16x32_bf16 v[132:135], v[136:139], v[160:163], v[132:135]
	v_mfma_f32_16x16x32_bf16 v[124:127], v[144:147], v[160:163], v[124:127]
	v_mfma_f32_16x16x32_bf16 v[100:103], v[136:139], v[168:171], v[100:103]
	v_mfma_f32_16x16x32_bf16 v[96:99], v[144:147], v[168:171], v[96:99]
	v_mfma_f32_16x16x32_bf16 v[84:87], v[136:139], v[176:179], v[84:87]
	v_mfma_f32_16x16x32_bf16 v[80:83], v[144:147], v[176:179], v[80:83]
	v_mfma_f32_16x16x32_bf16 v[68:71], v[136:139], v[184:187], v[68:71]
	v_mfma_f32_16x16x32_bf16 v[64:67], v[144:147], v[184:187], v[64:67]
	v_mfma_f32_16x16x32_bf16 v[132:135], v[140:143], v[164:167], v[132:135]
	v_mfma_f32_16x16x32_bf16 v[124:127], v[156:159], v[164:167], v[124:127]
	v_mfma_f32_16x16x32_bf16 v[100:103], v[140:143], v[172:175], v[100:103]
	v_mfma_f32_16x16x32_bf16 v[96:99], v[156:159], v[172:175], v[96:99]
	v_mfma_f32_16x16x32_bf16 v[84:87], v[140:143], v[180:183], v[84:87]
	v_mfma_f32_16x16x32_bf16 v[80:83], v[156:159], v[180:183], v[80:83]
	v_mfma_f32_16x16x32_bf16 v[68:71], v[140:143], v[204:207], v[68:71]
	v_mfma_f32_16x16x32_bf16 v[64:67], v[156:159], v[204:207], v[64:67]
	s_setprio 0
	s_barrier
	s_add_i32 s16, s71, s30
	v_lshl_add_u64 v[208:209], s[20:21], 0, v[200:201]
	s_mov_b32 m0, s16
	ds_read_b128 v[160:163], v226 offset:16384
	ds_read_b128 v[164:167], v226 offset:17408
	ds_read_b128 v[168:171], v226 offset:18432
	ds_read_b128 v[172:175], v226 offset:19456
	ds_read_b128 v[176:179], v226 offset:20480
	ds_read_b128 v[180:183], v226 offset:21504
	ds_read_b128 v[184:187], v226 offset:22528
	ds_read_b128 v[204:207], v226 offset:23552
	global_load_lds_dwordx4 v[208:209], off
	s_add_i32 m0, s16, 0x2000
	s_add_u32 s16, s20, 0x160000
	v_lshl_add_u64 v[210:211], s[20:21], 0, v[192:193]
	s_addc_u32 s17, s21, 0
	s_add_i32 s71, s72, s30
	global_load_lds_dwordx4 v[210:211], off
	v_lshl_add_u64 v[212:213], s[16:17], 0, v[200:201]
	s_mov_b32 m0, s71
	v_lshl_add_u64 v[214:215], s[22:23], 0, v[190:191]
	global_load_lds_dwordx4 v[212:213], off
	v_lshl_add_u64 v[212:213], s[16:17], 0, v[192:193]
	s_add_i32 m0, s71, 0x2000
	s_nop 0
	global_load_lds_dwordx4 v[212:213], off
	v_lshl_add_u64 v[212:213], s[22:23], 0, v[188:189]
	s_mov_b32 m0, s31
	s_nop 0
	global_load_lds_dwordx4 v[212:213], off
	s_mov_b32 m0, s34
	s_nop 0
	global_load_lds_dwordx4 v[214:215], off
	s_waitcnt vmcnt(8)
	s_waitcnt lgkmcnt(0)
	s_barrier
; #define PG8_STAGE(bufoff, gbase, voff) do { _Pragma("unroll") for (int _i = 0; _i < 2; ++_i) \
;         __builtin_amdgcn_global_load_lds((const unsigned*)((const char*)(gbase) + (voff)[_i]), (LAS unsigned*)(lds + (bufoff) + ldsw + _i * 8192), 16, 0, 0); } while (0)
; #define PG8_LDA(dst, b, h) do { _Pragma("unroll") for (int m = 0; m < 4; ++m) _Pragma("unroll") for (int k = 0; k < 2; ++k) dst[m][k] = *(const LAS bf16x8*)(lds + PG8_SA(b, h) + aoff + m * 2048 + k * 1024); } while (0)
; #define PG8_LDB(dst, b, h) do { _Pragma("unroll") for (int n = 0; n < 2; ++n) _Pragma("unroll") for (int k = 0; k < 2; ++k) dst[n][k] = *(const LAS bf16x8*)(lds + PG8_SB(b, h) + boff + n * 2048 + k * 1024); } while (0)
; #define PG8_MMA(ai, bj, At, Bt) do { __builtin_amdgcn_s_setprio(1); _Pragma("unroll") for (int m = 0; m < 4; ++m) _Pragma("unroll") for (int n = 0; n < 2; ++n) _Pragma("unroll") for (int k = 0; k < 2; ++k) \
;         acc[ai][bj][m][n] = __builtin_amdgcn_mfma_f32_16x16x32_bf16(Bt[n][k], At[m][k], acc[ai][bj][m][n], 0, 0, 0); __builtin_amdgcn_s_setprio(0); } while (0)
; #define PG8_WAIT_V(n) asm volatile("s_waitcnt vmcnt(" #n ")" ::: "memory")
; #define PG8_WAIT_L(n) asm volatile("s_waitcnt lgkmcnt(" #n ")" ::: "memory")
; #define PG8_BAR __builtin_amdgcn_s_barrier()
; #define PG8_SCHED __builtin_amdgcn_sched_barrier(0)
; template <class Epi, class Sched, bool APERM = false, bool HALFN = false>
; __device__ __forceinline__ void gemm_phase(LAS unsigned char* lds, const int tid_in, const int K, const Sched& S, const Epi& E) {
;     ...
;             PG8_WAIT_V(8); PG8_WAIT_L(0); PG8_BAR; PG8_MMA(1, 0, At, B0); if constexpr (!HALFN) PG8_MMA(1, 1, At, B1); PG8_BAR; PG8_SCHED;
;             PG8_LDB(B0, 1, 0); PG8_LDB(B1, 1, 1); PG8_SCHED; PG8_LDA(At, 1, 0); PG8_STAGE(PG8_SA(0, 1), a2 + hstepA, voffA);
;             PG8_WAIT_V(8); PG8_WAIT_L(0); PG8_BAR; PG8_MMA(0, 0, At, B0); if constexpr (!HALFN) PG8_MMA(0, 1, At, B1); PG8_BAR; PG8_SCHED;
	s_setprio 1
	v_mfma_f32_16x16x32_bf16 v[60:63], v[112:115], v[160:163], v[60:63]
	v_mfma_f32_16x16x32_bf16 v[56:59], v[120:123], v[160:163], v[56:59]
	v_mfma_f32_16x16x32_bf16 v[44:47], v[112:115], v[168:171], v[44:47]
	v_mfma_f32_16x16x32_bf16 v[40:43], v[120:123], v[168:171], v[40:43]
	v_mfma_f32_16x16x32_bf16 v[28:31], v[112:115], v[176:179], v[28:31]
	v_mfma_f32_16x16x32_bf16 v[24:27], v[120:123], v[176:179], v[24:27]
	v_mfma_f32_16x16x32_bf16 v[12:15], v[112:115], v[184:187], v[12:15]
	v_mfma_f32_16x16x32_bf16 v[8:11], v[120:123], v[184:187], v[8:11]
	v_mfma_f32_16x16x32_bf16 v[60:63], v[116:119], v[164:167], v[60:63]
	v_mfma_f32_16x16x32_bf16 v[56:59], v[128:131], v[164:167], v[56:59]
	v_mfma_f32_16x16x32_bf16 v[44:47], v[116:119], v[172:175], v[44:47]
	v_mfma_f32_16x16x32_bf16 v[40:43], v[128:131], v[172:175], v[40:43]
	v_mfma_f32_16x16x32_bf16 v[28:31], v[116:119], v[180:183], v[28:31]
	v_mfma_f32_16x16x32_bf16 v[24:27], v[128:131], v[180:183], v[24:27]
	v_mfma_f32_16x16x32_bf16 v[12:15], v[116:119], v[204:207], v[12:15]
	v_mfma_f32_16x16x32_bf16 v[8:11], v[128:131], v[204:207], v[8:11]
	v_mfma_f32_16x16x32_bf16 v[52:55], v[136:139], v[160:163], v[52:55]
	v_mfma_f32_16x16x32_bf16 v[48:51], v[144:147], v[160:163], v[48:51]
	v_mfma_f32_16x16x32_bf16 v[36:39], v[136:139], v[168:171], v[36:39]
	v_mfma_f32_16x16x32_bf16 v[32:35], v[144:147], v[168:171], v[32:35]
	v_mfma_f32_16x16x32_bf16 v[20:23], v[136:139], v[176:179], v[20:23]
	v_mfma_f32_16x16x32_bf16 v[16:19], v[144:147], v[176:179], v[16:19]
	v_mfma_f32_16x16x32_bf16 v[4:7], v[136:139], v[184:187], v[4:7]
	v_mfma_f32_16x16x32_bf16 v[0:3], v[144:147], v[184:187], v[0:3]
	v_mfma_f32_16x16x32_bf16 v[52:55], v[140:143], v[164:167], v[52:55]
	v_mfma_f32_16x16x32_bf16 v[48:51], v[156:159], v[164:167], v[48:51]
	v_mfma_f32_16x16x32_bf16 v[36:39], v[140:143], v[172:175], v[36:39]
	v_mfma_f32_16x16x32_bf16 v[32:35], v[156:159], v[172:175], v[32:35]
	v_mfma_f32_16x16x32_bf16 v[20:23], v[140:143], v[180:183], v[20:23]
	v_mfma_f32_16x16x32_bf16 v[16:19], v[156:159], v[180:183], v[16:19]
	v_mfma_f32_16x16x32_bf16 v[4:7], v[140:143], v[204:207], v[4:7]
	v_mfma_f32_16x16x32_bf16 v[0:3], v[156:159], v[204:207], v[0:3]
	s_setprio 0
	s_barrier
	s_add_i32 s71, 0, 0x18000
	s_add_i32 s72, 0, 0x1c000
	v_add_u32_e32 v128, s71, v220
	v_add_u32_e32 v156, s72, v220
	ds_read_b128 v[112:115], v128
	ds_read_b128 v[116:119], v128 offset:1024
	ds_read_b128 v[120:123], v128 offset:2048
	ds_read_b128 v[128:131], v128 offset:3072
	ds_read_b128 v[136:139], v156
	ds_read_b128 v[140:143], v156 offset:1024
	ds_read_b128 v[144:147], v156 offset:2048
	ds_read_b128 v[156:159], v156 offset:3072
	s_add_u32 s16, s22, 0x160000
	s_addc_u32 s17, s23, 0
	s_mov_b32 m0, s35
	v_lshl_add_u64 v[216:217], s[16:17], 0, v[188:189]
	ds_read_b128 v[160:163], v226 offset:32768
	ds_read_b128 v[164:167], v226 offset:33792
	ds_read_b128 v[168:171], v226 offset:34816
	ds_read_b128 v[172:175], v226 offset:35840
	ds_read_b128 v[176:179], v226 offset:36864
	ds_read_b128 v[180:183], v226 offset:37888
	ds_read_b128 v[184:187], v226 offset:38912
	ds_read_b128 v[204:207], v226 offset:39936
	global_load_lds_dwordx4 v[216:217], off
	v_lshl_add_u64 v[216:217], s[16:17], 0, v[190:191]
	s_mov_b32 m0, s38
	s_nop 0
	global_load_lds_dwordx4 v[216:217], off
	s_waitcnt vmcnt(8)
	s_waitcnt lgkmcnt(0)
	s_barrier
	s_setprio 1
	v_mfma_f32_16x16x32_bf16 v[152:155], v[112:115], v[160:163], v[152:155]
	v_mfma_f32_16x16x32_bf16 v[148:151], v[120:123], v[160:163], v[148:151]
	v_mfma_f32_16x16x32_bf16 v[108:111], v[112:115], v[168:171], v[108:111]
	v_mfma_f32_16x16x32_bf16 v[104:107], v[120:123], v[168:171], v[104:107]
	v_mfma_f32_16x16x32_bf16 v[92:95], v[112:115], v[176:179], v[92:95]
	v_mfma_f32_16x16x32_bf16 v[88:91], v[120:123], v[176:179], v[88:91]
	v_mfma_f32_16x16x32_bf16 v[76:79], v[112:115], v[184:187], v[76:79]
	v_mfma_f32_16x16x32_bf16 v[72:75], v[120:123], v[184:187], v[72:75]
	v_mfma_f32_16x16x32_bf16 v[152:155], v[116:119], v[164:167], v[152:155]
	v_mfma_f32_16x16x32_bf16 v[148:151], v[128:131], v[164:167], v[148:151]
	v_mfma_f32_16x16x32_bf16 v[108:111], v[116:119], v[172:175], v[108:111]
	v_mfma_f32_16x16x32_bf16 v[104:107], v[128:131], v[172:175], v[104:107]
	v_mfma_f32_16x16x32_bf16 v[92:95], v[116:119], v[180:183], v[92:95]
	v_mfma_f32_16x16x32_bf16 v[88:91], v[128:131], v[180:183], v[88:91]
	v_mfma_f32_16x16x32_bf16 v[76:79], v[116:119], v[204:207], v[76:79]
	v_mfma_f32_16x16x32_bf16 v[72:75], v[128:131], v[204:207], v[72:75]
	v_mfma_f32_16x16x32_bf16 v[132:135], v[136:139], v[160:163], v[132:135]
	v_mfma_f32_16x16x32_bf16 v[124:127], v[144:147], v[160:163], v[124:127]
	v_mfma_f32_16x16x32_bf16 v[100:103], v[136:139], v[168:171], v[100:103]
	v_mfma_f32_16x16x32_bf16 v[96:99], v[144:147], v[168:171], v[96:99]
	v_mfma_f32_16x16x32_bf16 v[84:87], v[136:139], v[176:179], v[84:87]
	v_mfma_f32_16x16x32_bf16 v[80:83], v[144:147], v[176:179], v[80:83]
	v_mfma_f32_16x16x32_bf16 v[68:71], v[136:139], v[184:187], v[68:71]
	v_mfma_f32_16x16x32_bf16 v[64:67], v[144:147], v[184:187], v[64:67]
	v_mfma_f32_16x16x32_bf16 v[132:135], v[140:143], v[164:167], v[132:135]
	v_mfma_f32_16x16x32_bf16 v[124:127], v[156:159], v[164:167], v[124:127]
	v_mfma_f32_16x16x32_bf16 v[100:103], v[140:143], v[172:175], v[100:103]
	v_mfma_f32_16x16x32_bf16 v[96:99], v[156:159], v[172:175], v[96:99]
	v_mfma_f32_16x16x32_bf16 v[84:87], v[140:143], v[180:183], v[84:87]
	v_mfma_f32_16x16x32_bf16 v[80:83], v[156:159], v[180:183], v[80:83]
	v_mfma_f32_16x16x32_bf16 v[68:71], v[140:143], v[204:207], v[68:71]
	v_mfma_f32_16x16x32_bf16 v[64:67], v[156:159], v[204:207], v[64:67]
	s_setprio 0
	s_barrier
; #define PG8_STAGE(bufoff, gbase, voff) do { _Pragma("unroll") for (int _i = 0; _i < 2; ++_i) \
;         __builtin_amdgcn_global_load_lds((const unsigned*)((const char*)(gbase) + (voff)[_i]), (LAS unsigned*)(lds + (bufoff) + ldsw + _i * 8192), 16, 0, 0); } while (0)
; #define PG8_LDA(dst, b, h) do { _Pragma("unroll") for (int m = 0; m < 4; ++m) _Pragma("unroll") for (int k = 0; k < 2; ++k) dst[m][k] = *(const LAS bf16x8*)(lds + PG8_SA(b, h) + aoff + m * 2048 + k * 1024); } while (0)
; #define PG8_MMA(ai, bj, At, Bt) do { __builtin_amdgcn_s_setprio(1); _Pragma("unroll") for (int m = 0; m < 4; ++m) _Pragma("unroll") for (int n = 0; n < 2; ++n) _Pragma("unroll") for (int k = 0; k < 2; ++k) \
;         acc[ai][bj][m][n] = __builtin_amdgcn_mfma_f32_16x16x32_bf16(Bt[n][k], At[m][k], acc[ai][bj][m][n], 0, 0, 0); __builtin_amdgcn_s_setprio(0); } while (0)
; #define PG8_WAIT_V(n) asm volatile("s_waitcnt vmcnt(" #n ")" ::: "memory")
; #define PG8_WAIT_L(n) asm volatile("s_waitcnt lgkmcnt(" #n ")" ::: "memory")
; #define PG8_BAR __builtin_amdgcn_s_barrier()
; #define PG8_SCHED __builtin_amdgcn_sched_barrier(0)
; template <class Epi, class Sched, bool APERM = false, bool HALFN = false>
; __device__ __forceinline__ void gemm_phase(LAS unsigned char* lds, const int tid_in, const int K, const Sched& S, const Epi& E) {
;     ...
;             PG8_LDA(At, 1, 1); PG8_STAGE(PG8_SB(1, 0), b3, voffB); PG8_STAGE(PG8_SB(1, 1), b3 + hstep, voffB); PG8_STAGE(PG8_SA(1, 0), a3, voffA);
;             PG8_WAIT_V(8); PG8_WAIT_L(0); PG8_BAR; PG8_MMA(1, 0, At, B0); if constexpr (!HALFN) PG8_MMA(1, 1, At, B1); PG8_BAR; PG8_SCHED;
;         }
;         if (wr == 0) PG8_BAR;
	s_add_i32 s16, s71, s30
	v_lshl_add_u64 v[208:209], v[208:209], 0, s[78:79]
	s_mov_b32 m0, s16
	ds_read_b128 v[160:163], v226 offset:49152
	ds_read_b128 v[164:167], v226 offset:50176
	ds_read_b128 v[168:171], v226 offset:51200
	ds_read_b128 v[172:175], v226 offset:52224
	ds_read_b128 v[176:179], v226 offset:53248
	ds_read_b128 v[180:183], v226 offset:54272
	ds_read_b128 v[184:187], v226 offset:55296
	ds_read_b128 v[204:207], v226 offset:56320
	global_load_lds_dwordx4 v[208:209], off
	s_add_i32 m0, s16, 0x2000
	s_add_u32 s16, s20, 0x160080
	v_lshl_add_u64 v[208:209], v[210:211], 0, s[78:79]
	s_addc_u32 s17, s21, 0
	s_add_i32 s20, s72, s30
	global_load_lds_dwordx4 v[208:209], off
	v_lshl_add_u64 v[208:209], s[16:17], 0, v[200:201]
	s_mov_b32 m0, s20
	s_nop 0
	global_load_lds_dwordx4 v[208:209], off
	v_lshl_add_u64 v[208:209], s[16:17], 0, v[192:193]
	s_add_i32 m0, s20, 0x2000
	s_nop 0
	global_load_lds_dwordx4 v[208:209], off
	v_lshl_add_u64 v[208:209], v[212:213], 0, s[78:79]
	s_mov_b32 m0, s39
	s_nop 0
	global_load_lds_dwordx4 v[208:209], off
	v_lshl_add_u64 v[208:209], v[214:215], 0, s[78:79]
	s_mov_b32 m0, s44
	s_nop 0
	global_load_lds_dwordx4 v[208:209], off
	s_waitcnt vmcnt(8)
	s_waitcnt lgkmcnt(0)
	s_barrier
	s_setprio 1
	v_mfma_f32_16x16x32_bf16 v[60:63], v[112:115], v[160:163], v[60:63]
	v_mfma_f32_16x16x32_bf16 v[56:59], v[120:123], v[160:163], v[56:59]
	v_mfma_f32_16x16x32_bf16 v[44:47], v[112:115], v[168:171], v[44:47]
	v_mfma_f32_16x16x32_bf16 v[40:43], v[120:123], v[168:171], v[40:43]
	v_mfma_f32_16x16x32_bf16 v[28:31], v[112:115], v[176:179], v[28:31]
	v_mfma_f32_16x16x32_bf16 v[24:27], v[120:123], v[176:179], v[24:27]
	v_mfma_f32_16x16x32_bf16 v[12:15], v[112:115], v[184:187], v[12:15]
	v_mfma_f32_16x16x32_bf16 v[8:11], v[120:123], v[184:187], v[8:11]
	v_mfma_f32_16x16x32_bf16 v[60:63], v[116:119], v[164:167], v[60:63]
	v_mfma_f32_16x16x32_bf16 v[56:59], v[128:131], v[164:167], v[56:59]
	v_mfma_f32_16x16x32_bf16 v[44:47], v[116:119], v[172:175], v[44:47]
	v_mfma_f32_16x16x32_bf16 v[40:43], v[128:131], v[172:175], v[40:43]
	v_mfma_f32_16x16x32_bf16 v[28:31], v[116:119], v[180:183], v[28:31]
	v_mfma_f32_16x16x32_bf16 v[24:27], v[128:131], v[180:183], v[24:27]
	v_mfma_f32_16x16x32_bf16 v[12:15], v[116:119], v[204:207], v[12:15]
	v_mfma_f32_16x16x32_bf16 v[8:11], v[128:131], v[204:207], v[8:11]
	v_mfma_f32_16x16x32_bf16 v[52:55], v[136:139], v[160:163], v[52:55]
	v_mfma_f32_16x16x32_bf16 v[48:51], v[144:147], v[160:163], v[48:51]
	v_mfma_f32_16x16x32_bf16 v[36:39], v[136:139], v[168:171], v[36:39]
	v_mfma_f32_16x16x32_bf16 v[32:35], v[144:147], v[168:171], v[32:35]
	v_mfma_f32_16x16x32_bf16 v[20:23], v[136:139], v[176:179], v[20:23]
	v_mfma_f32_16x16x32_bf16 v[16:19], v[144:147], v[176:179], v[16:19]
	v_mfma_f32_16x16x32_bf16 v[4:7], v[136:139], v[184:187], v[4:7]
	v_mfma_f32_16x16x32_bf16 v[0:3], v[144:147], v[184:187], v[0:3]
	v_mfma_f32_16x16x32_bf16 v[52:55], v[140:143], v[164:167], v[52:55]
	v_mfma_f32_16x16x32_bf16 v[48:51], v[156:159], v[164:167], v[48:51]
	v_mfma_f32_16x16x32_bf16 v[36:39], v[140:143], v[172:175], v[36:39]
	v_mfma_f32_16x16x32_bf16 v[32:35], v[156:159], v[172:175], v[32:35]
	v_mfma_f32_16x16x32_bf16 v[20:23], v[140:143], v[180:183], v[20:23]
	v_mfma_f32_16x16x32_bf16 v[16:19], v[156:159], v[180:183], v[16:19]
	v_mfma_f32_16x16x32_bf16 v[4:7], v[140:143], v[204:207], v[4:7]
	v_mfma_f32_16x16x32_bf16 v[0:3], v[156:159], v[204:207], v[0:3]
	s_setprio 0
	s_barrier
	s_add_i32 s70, s70, 2
	s_add_u32 s53, s53, 0x100
	s_addc_u32 s57, s57, 0
	s_cmpk_gt_u32 s70, 0x55
	s_mov_b64 s[16:17], s[18:19]
	s_cbranch_scc0 .LBB0_1033
	s_and_b64 vcc, exec, s[8:9]
	s_cbranch_vccz .LBB0_1036
	s_barrier
